# GEMM K-loops: redundant compiler lgkmcnt(0) after the pre-MFMA barrier removed (explicit wait before the barrier already drains LDS)
# speedup vs baseline: 1.0049x; 1.0001x over previous
.LBB0_224:
	s_add_u32 s44, s38, 0x100
	s_addc_u32 s45, s39, 0
	s_add_i32 s30, 0, 0x10000
	s_cmp_eq_u32 s73, 12
	s_cselect_b32 s49, s9, s45
	s_cselect_b32 s48, s11, s44
	v_add_u32_e32 v138, s30, v141
	s_cselect_b32 s47, s20, s29
	s_cselect_b32 s46, s21, s27
	s_add_i32 s83, 0, 0x14000
	ds_read_b128 v[148:151], v138
	ds_read_b128 v[152:155], v138 offset:1024
	ds_read_b128 v[156:159], v138 offset:2048
	ds_read_b128 v[160:163], v138 offset:3072
	v_add_u32_e32 v138, s83, v141
	ds_read_b128 v[164:167], v138
	ds_read_b128 v[168:171], v138 offset:1024
	ds_read_b128 v[172:175], v138 offset:2048
	ds_read_b128 v[198:201], v138 offset:3072
	v_lshl_add_u64 v[138:139], s[38:39], 0, v[136:137]
	s_add_i32 m0, s40, 0xc000
	ds_read_b128 v[202:205], v145
	ds_read_b128 v[206:209], v145 offset:1024
	ds_read_b128 v[210:213], v145 offset:2048
	ds_read_b128 v[214:217], v145 offset:3072
	ds_read_b128 v[218:221], v145 offset:4096
	ds_read_b128 v[222:225], v145 offset:5120
	ds_read_b128 v[226:229], v145 offset:6144
	ds_read_b128 v[238:241], v145 offset:7168
	global_load_lds_dwordx4 v[138:139], off
	v_lshl_add_u64 v[138:139], s[38:39], 0, v[134:135]
	s_add_i32 m0, s40, 0xe000
	s_nop 0
	global_load_lds_dwordx4 v[138:139], off
	s_waitcnt vmcnt(8)
	s_waitcnt lgkmcnt(0)
	s_barrier
	s_setprio 1
	v_mfma_f32_16x16x32_bf16 v[124:127], v[148:151], v[202:205], v[124:127]
	v_mfma_f32_16x16x32_bf16 v[120:123], v[156:159], v[202:205], v[120:123]
	v_mfma_f32_16x16x32_bf16 v[116:119], v[148:151], v[210:213], v[116:119]
	v_mfma_f32_16x16x32_bf16 v[112:115], v[156:159], v[210:213], v[112:115]
	v_mfma_f32_16x16x32_bf16 v[108:111], v[148:151], v[218:221], v[108:111]
	v_mfma_f32_16x16x32_bf16 v[104:107], v[156:159], v[218:221], v[104:107]
	v_mfma_f32_16x16x32_bf16 v[100:103], v[148:151], v[226:229], v[100:103]
	v_mfma_f32_16x16x32_bf16 v[96:99], v[156:159], v[226:229], v[96:99]
	v_mfma_f32_16x16x32_bf16 v[124:127], v[152:155], v[206:209], v[124:127]
	v_mfma_f32_16x16x32_bf16 v[120:123], v[160:163], v[206:209], v[120:123]
	v_mfma_f32_16x16x32_bf16 v[116:119], v[152:155], v[214:217], v[116:119]
	v_mfma_f32_16x16x32_bf16 v[112:115], v[160:163], v[214:217], v[112:115]
	v_mfma_f32_16x16x32_bf16 v[108:111], v[152:155], v[222:225], v[108:111]
	v_mfma_f32_16x16x32_bf16 v[104:107], v[160:163], v[222:225], v[104:107]
	v_mfma_f32_16x16x32_bf16 v[100:103], v[152:155], v[238:241], v[100:103]
	v_mfma_f32_16x16x32_bf16 v[96:99], v[160:163], v[238:241], v[96:99]
	v_mfma_f32_16x16x32_bf16 v[60:63], v[164:167], v[202:205], v[60:63]
	v_mfma_f32_16x16x32_bf16 v[56:59], v[172:175], v[202:205], v[56:59]
	v_mfma_f32_16x16x32_bf16 v[52:55], v[164:167], v[210:213], v[52:55]
	v_mfma_f32_16x16x32_bf16 v[48:51], v[172:175], v[210:213], v[48:51]
	v_mfma_f32_16x16x32_bf16 v[44:47], v[164:167], v[218:221], v[44:47]
	v_mfma_f32_16x16x32_bf16 v[40:43], v[172:175], v[218:221], v[40:43]
	v_mfma_f32_16x16x32_bf16 v[36:39], v[164:167], v[226:229], v[36:39]
	v_mfma_f32_16x16x32_bf16 v[32:35], v[172:175], v[226:229], v[32:35]
	v_mfma_f32_16x16x32_bf16 v[60:63], v[168:171], v[206:209], v[60:63]
	v_mfma_f32_16x16x32_bf16 v[56:59], v[198:201], v[206:209], v[56:59]
	v_mfma_f32_16x16x32_bf16 v[52:55], v[168:171], v[214:217], v[52:55]
	v_mfma_f32_16x16x32_bf16 v[48:51], v[198:201], v[214:217], v[48:51]
	v_mfma_f32_16x16x32_bf16 v[44:47], v[168:171], v[222:225], v[44:47]
	v_mfma_f32_16x16x32_bf16 v[40:43], v[198:201], v[222:225], v[40:43]
	v_mfma_f32_16x16x32_bf16 v[36:39], v[168:171], v[238:241], v[36:39]
	v_mfma_f32_16x16x32_bf16 v[32:35], v[198:201], v[238:241], v[32:35]
	s_setprio 0
	s_barrier
	s_add_i32 s30, s30, s5
	v_lshl_add_u64 v[138:139], s[46:47], 0, v[130:131]
	s_mov_b32 m0, s30
	ds_read_b128 v[202:205], v145 offset:16384
	ds_read_b128 v[206:209], v145 offset:17408
	ds_read_b128 v[210:213], v145 offset:18432
	ds_read_b128 v[214:217], v145 offset:19456
	ds_read_b128 v[218:221], v145 offset:20480
	ds_read_b128 v[222:225], v145 offset:21504
	ds_read_b128 v[226:229], v145 offset:22528
	ds_read_b128 v[238:241], v145 offset:23552
	global_load_lds_dwordx4 v[138:139], off
	s_add_i32 m0, s30, 0x2000
	s_add_u32 s30, s46, 0x40000
	v_lshl_add_u64 v[176:177], s[46:47], 0, v[132:133]
	s_addc_u32 s31, s47, 0
	s_add_i32 s38, s83, s5
	global_load_lds_dwordx4 v[176:177], off
	v_lshl_add_u64 v[242:243], s[30:31], 0, v[130:131]
	s_mov_b32 m0, s38
	v_lshl_add_u64 v[244:245], s[48:49], 0, v[132:133]
	global_load_lds_dwordx4 v[242:243], off
	v_lshl_add_u64 v[242:243], s[30:31], 0, v[132:133]
	s_add_i32 m0, s38, 0x2000
	s_nop 0
	global_load_lds_dwordx4 v[242:243], off
	v_lshl_add_u64 v[242:243], s[48:49], 0, v[130:131]
	s_mov_b32 m0, s40
	s_nop 0
	global_load_lds_dwordx4 v[242:243], off
	s_mov_b32 m0, s41
	s_nop 0
	global_load_lds_dwordx4 v[244:245], off
	s_waitcnt vmcnt(8)
	s_waitcnt lgkmcnt(0)
	s_barrier
	s_setprio 1
	v_mfma_f32_16x16x32_bf16 v[92:95], v[148:151], v[202:205], v[92:95]
	v_mfma_f32_16x16x32_bf16 v[88:91], v[156:159], v[202:205], v[88:91]
	v_mfma_f32_16x16x32_bf16 v[84:87], v[148:151], v[210:213], v[84:87]
	v_mfma_f32_16x16x32_bf16 v[80:83], v[156:159], v[210:213], v[80:83]
	v_mfma_f32_16x16x32_bf16 v[76:79], v[148:151], v[218:221], v[76:79]
	v_mfma_f32_16x16x32_bf16 v[72:75], v[156:159], v[218:221], v[72:75]
	v_mfma_f32_16x16x32_bf16 v[68:71], v[148:151], v[226:229], v[68:71]
	v_mfma_f32_16x16x32_bf16 v[64:67], v[156:159], v[226:229], v[64:67]
	v_mfma_f32_16x16x32_bf16 v[92:95], v[152:155], v[206:209], v[92:95]
	v_mfma_f32_16x16x32_bf16 v[88:91], v[160:163], v[206:209], v[88:91]
	v_mfma_f32_16x16x32_bf16 v[84:87], v[152:155], v[214:217], v[84:87]
	v_mfma_f32_16x16x32_bf16 v[80:83], v[160:163], v[214:217], v[80:83]
	v_mfma_f32_16x16x32_bf16 v[76:79], v[152:155], v[222:225], v[76:79]
	v_mfma_f32_16x16x32_bf16 v[72:75], v[160:163], v[222:225], v[72:75]
	v_mfma_f32_16x16x32_bf16 v[68:71], v[152:155], v[238:241], v[68:71]
	v_mfma_f32_16x16x32_bf16 v[64:67], v[160:163], v[238:241], v[64:67]
	v_mfma_f32_16x16x32_bf16 v[28:31], v[164:167], v[202:205], v[28:31]
	v_mfma_f32_16x16x32_bf16 v[24:27], v[172:175], v[202:205], v[24:27]
	v_mfma_f32_16x16x32_bf16 v[20:23], v[164:167], v[210:213], v[20:23]
	v_mfma_f32_16x16x32_bf16 v[16:19], v[172:175], v[210:213], v[16:19]
	v_mfma_f32_16x16x32_bf16 v[12:15], v[164:167], v[218:221], v[12:15]
	v_mfma_f32_16x16x32_bf16 v[8:11], v[172:175], v[218:221], v[8:11]
	v_mfma_f32_16x16x32_bf16 v[4:7], v[164:167], v[226:229], v[4:7]
	v_mfma_f32_16x16x32_bf16 v[0:3], v[172:175], v[226:229], v[0:3]
	v_mfma_f32_16x16x32_bf16 v[28:31], v[168:171], v[206:209], v[28:31]
	v_mfma_f32_16x16x32_bf16 v[24:27], v[198:201], v[206:209], v[24:27]
	v_mfma_f32_16x16x32_bf16 v[20:23], v[168:171], v[214:217], v[20:23]
	v_mfma_f32_16x16x32_bf16 v[16:19], v[198:201], v[214:217], v[16:19]
	v_mfma_f32_16x16x32_bf16 v[12:15], v[168:171], v[222:225], v[12:15]
	v_mfma_f32_16x16x32_bf16 v[8:11], v[198:201], v[222:225], v[8:11]
	v_mfma_f32_16x16x32_bf16 v[4:7], v[168:171], v[238:241], v[4:7]
	v_mfma_f32_16x16x32_bf16 v[0:3], v[198:201], v[238:241], v[0:3]
	s_setprio 0
	s_barrier
	s_add_i32 s38, 0, 0x18000
	v_add_u32_e32 v147, s38, v141
	s_add_i32 s39, 0, 0x1c000
	ds_read_b128 v[148:151], v147
	ds_read_b128 v[152:155], v147 offset:1024
	ds_read_b128 v[156:159], v147 offset:2048
	ds_read_b128 v[160:163], v147 offset:3072
	v_add_u32_e32 v147, s39, v141
	ds_read_b128 v[164:167], v147
	ds_read_b128 v[168:171], v147 offset:1024
	ds_read_b128 v[172:175], v147 offset:2048
	ds_read_b128 v[198:201], v147 offset:3072
	s_add_u32 s30, s48, 0x40000
	s_addc_u32 s31, s49, 0
	s_mov_b32 m0, s42
	v_lshl_add_u64 v[246:247], s[30:31], 0, v[130:131]
	ds_read_b128 v[202:205], v145 offset:32768
	ds_read_b128 v[206:209], v145 offset:33792
	ds_read_b128 v[210:213], v145 offset:34816
	ds_read_b128 v[214:217], v145 offset:35840
	ds_read_b128 v[218:221], v145 offset:36864
	ds_read_b128 v[222:225], v145 offset:37888
	ds_read_b128 v[226:229], v145 offset:38912
	ds_read_b128 v[238:241], v145 offset:39936
	global_load_lds_dwordx4 v[246:247], off
	v_lshl_add_u64 v[246:247], s[30:31], 0, v[132:133]
	s_mov_b32 m0, s43
	s_nop 0
	global_load_lds_dwordx4 v[246:247], off
	s_waitcnt vmcnt(8)
	s_waitcnt lgkmcnt(0)
	s_barrier
	s_setprio 1
	v_mfma_f32_16x16x32_bf16 v[124:127], v[148:151], v[202:205], v[124:127]
	v_mfma_f32_16x16x32_bf16 v[120:123], v[156:159], v[202:205], v[120:123]
	v_mfma_f32_16x16x32_bf16 v[116:119], v[148:151], v[210:213], v[116:119]
	v_mfma_f32_16x16x32_bf16 v[112:115], v[156:159], v[210:213], v[112:115]
	v_mfma_f32_16x16x32_bf16 v[108:111], v[148:151], v[218:221], v[108:111]
	v_mfma_f32_16x16x32_bf16 v[104:107], v[156:159], v[218:221], v[104:107]
	v_mfma_f32_16x16x32_bf16 v[100:103], v[148:151], v[226:229], v[100:103]
	v_mfma_f32_16x16x32_bf16 v[96:99], v[156:159], v[226:229], v[96:99]
	v_mfma_f32_16x16x32_bf16 v[124:127], v[152:155], v[206:209], v[124:127]
	v_mfma_f32_16x16x32_bf16 v[120:123], v[160:163], v[206:209], v[120:123]
	v_mfma_f32_16x16x32_bf16 v[116:119], v[152:155], v[214:217], v[116:119]
	v_mfma_f32_16x16x32_bf16 v[112:115], v[160:163], v[214:217], v[112:115]
	v_mfma_f32_16x16x32_bf16 v[108:111], v[152:155], v[222:225], v[108:111]
	v_mfma_f32_16x16x32_bf16 v[104:107], v[160:163], v[222:225], v[104:107]
	v_mfma_f32_16x16x32_bf16 v[100:103], v[152:155], v[238:241], v[100:103]
	v_mfma_f32_16x16x32_bf16 v[96:99], v[160:163], v[238:241], v[96:99]
	v_mfma_f32_16x16x32_bf16 v[60:63], v[164:167], v[202:205], v[60:63]
	v_mfma_f32_16x16x32_bf16 v[56:59], v[172:175], v[202:205], v[56:59]
	v_mfma_f32_16x16x32_bf16 v[52:55], v[164:167], v[210:213], v[52:55]
	v_mfma_f32_16x16x32_bf16 v[48:51], v[172:175], v[210:213], v[48:51]
	v_mfma_f32_16x16x32_bf16 v[44:47], v[164:167], v[218:221], v[44:47]
	v_mfma_f32_16x16x32_bf16 v[40:43], v[172:175], v[218:221], v[40:43]
	v_mfma_f32_16x16x32_bf16 v[36:39], v[164:167], v[226:229], v[36:39]
	v_mfma_f32_16x16x32_bf16 v[32:35], v[172:175], v[226:229], v[32:35]
	v_mfma_f32_16x16x32_bf16 v[60:63], v[168:171], v[206:209], v[60:63]
	v_mfma_f32_16x16x32_bf16 v[56:59], v[198:201], v[206:209], v[56:59]
	v_mfma_f32_16x16x32_bf16 v[52:55], v[168:171], v[214:217], v[52:55]
	v_mfma_f32_16x16x32_bf16 v[48:51], v[198:201], v[214:217], v[48:51]
	v_mfma_f32_16x16x32_bf16 v[44:47], v[168:171], v[222:225], v[44:47]
	v_mfma_f32_16x16x32_bf16 v[40:43], v[198:201], v[222:225], v[40:43]
	v_mfma_f32_16x16x32_bf16 v[36:39], v[168:171], v[238:241], v[36:39]
	v_mfma_f32_16x16x32_bf16 v[32:35], v[198:201], v[238:241], v[32:35]
	s_setprio 0
	s_barrier
	s_add_i32 s30, s38, s5
	v_lshl_add_u64 v[138:139], v[138:139], 0, s[90:91]
	s_mov_b32 m0, s30
	ds_read_b128 v[202:205], v145 offset:49152
	ds_read_b128 v[206:209], v145 offset:50176
	ds_read_b128 v[210:213], v145 offset:51200
	ds_read_b128 v[214:217], v145 offset:52224
	ds_read_b128 v[218:221], v145 offset:53248
	ds_read_b128 v[222:225], v145 offset:54272
	ds_read_b128 v[226:229], v145 offset:55296
	ds_read_b128 v[238:241], v145 offset:56320
	global_load_lds_dwordx4 v[138:139], off
	s_add_i32 m0, s30, 0x2000
	s_add_u32 s30, s46, 0x40080
	v_lshl_add_u64 v[138:139], v[176:177], 0, s[90:91]
	s_addc_u32 s31, s47, 0
	s_add_i32 s38, s39, s5
	global_load_lds_dwordx4 v[138:139], off
	v_lshl_add_u64 v[138:139], s[30:31], 0, v[130:131]
	s_mov_b32 m0, s38
	s_nop 0
	global_load_lds_dwordx4 v[138:139], off
	v_lshl_add_u64 v[138:139], s[30:31], 0, v[132:133]
	s_add_i32 m0, s38, 0x2000
	s_nop 0
	global_load_lds_dwordx4 v[138:139], off
	v_lshl_add_u64 v[138:139], v[242:243], 0, s[90:91]
	s_mov_b32 m0, s55
	s_nop 0
	global_load_lds_dwordx4 v[138:139], off
	v_lshl_add_u64 v[138:139], v[244:245], 0, s[90:91]
	s_mov_b32 m0, s56
	s_nop 0
	global_load_lds_dwordx4 v[138:139], off
	s_waitcnt vmcnt(8)
	s_waitcnt lgkmcnt(0)
	s_barrier
	s_setprio 1
	v_mfma_f32_16x16x32_bf16 v[92:95], v[148:151], v[202:205], v[92:95]
	v_mfma_f32_16x16x32_bf16 v[88:91], v[156:159], v[202:205], v[88:91]
	v_mfma_f32_16x16x32_bf16 v[84:87], v[148:151], v[210:213], v[84:87]
	v_mfma_f32_16x16x32_bf16 v[80:83], v[156:159], v[210:213], v[80:83]
	v_mfma_f32_16x16x32_bf16 v[76:79], v[148:151], v[218:221], v[76:79]
	v_mfma_f32_16x16x32_bf16 v[72:75], v[156:159], v[218:221], v[72:75]
	v_mfma_f32_16x16x32_bf16 v[68:71], v[148:151], v[226:229], v[68:71]
	v_mfma_f32_16x16x32_bf16 v[64:67], v[156:159], v[226:229], v[64:67]
	v_mfma_f32_16x16x32_bf16 v[92:95], v[152:155], v[206:209], v[92:95]
	v_mfma_f32_16x16x32_bf16 v[88:91], v[160:163], v[206:209], v[88:91]
	v_mfma_f32_16x16x32_bf16 v[84:87], v[152:155], v[214:217], v[84:87]
	v_mfma_f32_16x16x32_bf16 v[80:83], v[160:163], v[214:217], v[80:83]
	v_mfma_f32_16x16x32_bf16 v[76:79], v[152:155], v[222:225], v[76:79]
	v_mfma_f32_16x16x32_bf16 v[72:75], v[160:163], v[222:225], v[72:75]
	v_mfma_f32_16x16x32_bf16 v[68:71], v[152:155], v[238:241], v[68:71]
	v_mfma_f32_16x16x32_bf16 v[64:67], v[160:163], v[238:241], v[64:67]
	v_mfma_f32_16x16x32_bf16 v[28:31], v[164:167], v[202:205], v[28:31]
	v_mfma_f32_16x16x32_bf16 v[24:27], v[172:175], v[202:205], v[24:27]
	v_mfma_f32_16x16x32_bf16 v[20:23], v[164:167], v[210:213], v[20:23]
	v_mfma_f32_16x16x32_bf16 v[16:19], v[172:175], v[210:213], v[16:19]
	v_mfma_f32_16x16x32_bf16 v[12:15], v[164:167], v[218:221], v[12:15]
	v_mfma_f32_16x16x32_bf16 v[8:11], v[172:175], v[218:221], v[8:11]
	v_mfma_f32_16x16x32_bf16 v[4:7], v[164:167], v[226:229], v[4:7]
	v_mfma_f32_16x16x32_bf16 v[0:3], v[172:175], v[226:229], v[0:3]
	v_mfma_f32_16x16x32_bf16 v[28:31], v[168:171], v[206:209], v[28:31]
	v_mfma_f32_16x16x32_bf16 v[24:27], v[198:201], v[206:209], v[24:27]
	v_mfma_f32_16x16x32_bf16 v[20:23], v[168:171], v[214:217], v[20:23]
	v_mfma_f32_16x16x32_bf16 v[16:19], v[198:201], v[214:217], v[16:19]
	v_mfma_f32_16x16x32_bf16 v[12:15], v[168:171], v[222:225], v[12:15]
	v_mfma_f32_16x16x32_bf16 v[8:11], v[198:201], v[222:225], v[8:11]
	v_mfma_f32_16x16x32_bf16 v[4:7], v[168:171], v[238:241], v[4:7]
	v_mfma_f32_16x16x32_bf16 v[0:3], v[198:201], v[238:241], v[0:3]
	s_setprio 0
	s_barrier
	s_add_i32 s73, s73, 2
	s_add_u32 s27, s27, 0x100
	s_addc_u32 s29, s29, 0
	s_cmp_gt_u32 s73, 13
	s_mov_b64 s[38:39], s[44:45]
	s_cbranch_scc0 .LBB0_224
	s_and_b64 vcc, exec, s[24:25]
	s_cbranch_vccz .LBB0_227
	s_barrier

.LBB0_273:
	s_add_u32 s30, s28, 0xfffc0080
	s_addc_u32 s31, s29, -1
	s_add_i32 s59, 0, 0x10000
	s_cmp_eq_u32 s58, 12
	s_cselect_b32 s45, s27, s31
	s_cselect_b32 s44, s53, s30
	v_add_u32_e32 v142, s59, v145
	s_cselect_b32 s35, s25, s57
	s_cselect_b32 s34, s55, s56
	s_add_i32 s60, 0, 0x14000
	ds_read_b128 v[146:149], v142
	ds_read_b128 v[150:153], v142 offset:1024
	ds_read_b128 v[154:157], v142 offset:2048
	ds_read_b128 v[158:161], v142 offset:3072
	v_add_u32_e32 v142, s60, v145
	ds_read_b128 v[162:165], v142
	ds_read_b128 v[166:169], v142 offset:1024
	ds_read_b128 v[170:173], v142 offset:2048
	ds_read_b128 v[174:177], v142 offset:3072
	v_lshl_add_u64 v[142:143], s[28:29], 0, v[138:139]
	s_add_i32 m0, s19, 0xc000
	ds_read_b128 v[198:201], v141
	ds_read_b128 v[202:205], v141 offset:1024
	ds_read_b128 v[206:209], v141 offset:2048
	ds_read_b128 v[210:213], v141 offset:3072
	ds_read_b128 v[214:217], v141 offset:4096
	ds_read_b128 v[218:221], v141 offset:5120
	ds_read_b128 v[222:225], v141 offset:6144
	ds_read_b128 v[226:229], v141 offset:7168
	global_load_lds_dwordx4 v[142:143], off
	v_lshl_add_u64 v[142:143], s[28:29], 0, v[136:137]
	s_add_i32 m0, s19, 0xe000
	s_nop 0
	global_load_lds_dwordx4 v[142:143], off
	s_waitcnt vmcnt(8)
	s_waitcnt lgkmcnt(0)
	s_barrier
	s_setprio 1
	v_mfma_f32_16x16x32_bf16 v[108:111], v[146:149], v[198:201], v[108:111]
	v_mfma_f32_16x16x32_bf16 v[116:119], v[154:157], v[198:201], v[116:119]
	v_mfma_f32_16x16x32_bf16 v[92:95], v[146:149], v[206:209], v[92:95]
	v_mfma_f32_16x16x32_bf16 v[100:103], v[154:157], v[206:209], v[100:103]
	v_mfma_f32_16x16x32_bf16 v[68:71], v[146:149], v[214:217], v[68:71]
	v_mfma_f32_16x16x32_bf16 v[76:79], v[154:157], v[214:217], v[76:79]
	v_mfma_f32_16x16x32_bf16 v[40:43], v[146:149], v[222:225], v[40:43]
	v_mfma_f32_16x16x32_bf16 v[44:47], v[154:157], v[222:225], v[44:47]
	v_mfma_f32_16x16x32_bf16 v[108:111], v[150:153], v[202:205], v[108:111]
	v_mfma_f32_16x16x32_bf16 v[116:119], v[158:161], v[202:205], v[116:119]
	v_mfma_f32_16x16x32_bf16 v[92:95], v[150:153], v[210:213], v[92:95]
	v_mfma_f32_16x16x32_bf16 v[100:103], v[158:161], v[210:213], v[100:103]
	v_mfma_f32_16x16x32_bf16 v[68:71], v[150:153], v[218:221], v[68:71]
	v_mfma_f32_16x16x32_bf16 v[76:79], v[158:161], v[218:221], v[76:79]
	v_mfma_f32_16x16x32_bf16 v[40:43], v[150:153], v[226:229], v[40:43]
	v_mfma_f32_16x16x32_bf16 v[44:47], v[158:161], v[226:229], v[44:47]
	v_mfma_f32_16x16x32_bf16 v[120:123], v[162:165], v[198:201], v[120:123]
	v_mfma_f32_16x16x32_bf16 v[124:127], v[170:173], v[198:201], v[124:127]
	v_mfma_f32_16x16x32_bf16 v[104:107], v[162:165], v[206:209], v[104:107]
	v_mfma_f32_16x16x32_bf16 v[112:115], v[170:173], v[206:209], v[112:115]
	v_mfma_f32_16x16x32_bf16 v[88:91], v[162:165], v[214:217], v[88:91]
	v_mfma_f32_16x16x32_bf16 v[96:99], v[170:173], v[214:217], v[96:99]
	v_mfma_f32_16x16x32_bf16 v[64:67], v[162:165], v[222:225], v[64:67]
	v_mfma_f32_16x16x32_bf16 v[72:75], v[170:173], v[222:225], v[72:75]
	v_mfma_f32_16x16x32_bf16 v[120:123], v[166:169], v[202:205], v[120:123]
	v_mfma_f32_16x16x32_bf16 v[124:127], v[174:177], v[202:205], v[124:127]
	v_mfma_f32_16x16x32_bf16 v[104:107], v[166:169], v[210:213], v[104:107]
	v_mfma_f32_16x16x32_bf16 v[112:115], v[174:177], v[210:213], v[112:115]
	v_mfma_f32_16x16x32_bf16 v[88:91], v[166:169], v[218:221], v[88:91]
	v_mfma_f32_16x16x32_bf16 v[96:99], v[174:177], v[218:221], v[96:99]
	v_mfma_f32_16x16x32_bf16 v[64:67], v[166:169], v[226:229], v[64:67]
	v_mfma_f32_16x16x32_bf16 v[72:75], v[174:177], v[226:229], v[72:75]
	s_setprio 0
	s_barrier
	s_add_i32 s30, s59, s4
	v_lshl_add_u64 v[142:143], s[34:35], 0, v[128:129]
	s_mov_b32 m0, s30
	ds_read_b128 v[198:201], v141 offset:16384
	ds_read_b128 v[202:205], v141 offset:17408
	ds_read_b128 v[206:209], v141 offset:18432
	ds_read_b128 v[210:213], v141 offset:19456
	ds_read_b128 v[214:217], v141 offset:20480
	ds_read_b128 v[218:221], v141 offset:21504
	ds_read_b128 v[222:225], v141 offset:22528
	ds_read_b128 v[226:229], v141 offset:23552
	global_load_lds_dwordx4 v[142:143], off
	s_add_i32 m0, s30, 0x2000
	s_add_u32 s30, s34, 0x40000
	v_lshl_add_u64 v[238:239], s[34:35], 0, v[130:131]
	s_addc_u32 s31, s35, 0
	s_add_i32 s59, s60, s4
	global_load_lds_dwordx4 v[238:239], off
	v_lshl_add_u64 v[240:241], s[30:31], 0, v[128:129]
	s_mov_b32 m0, s59
	v_lshl_add_u64 v[242:243], s[44:45], 0, v[132:133]
	global_load_lds_dwordx4 v[240:241], off
	v_lshl_add_u64 v[240:241], s[30:31], 0, v[130:131]
	s_add_i32 m0, s59, 0x2000
	s_nop 0
	global_load_lds_dwordx4 v[240:241], off
	v_lshl_add_u64 v[240:241], s[44:45], 0, v[134:135]
	s_mov_b32 m0, s19
	s_nop 0
	global_load_lds_dwordx4 v[240:241], off
	s_mov_b32 m0, s43
	s_nop 0
	global_load_lds_dwordx4 v[242:243], off
	s_waitcnt vmcnt(8)
	s_waitcnt lgkmcnt(0)
	s_barrier
	s_setprio 1
	v_mfma_f32_16x16x32_bf16 v[52:55], v[146:149], v[198:201], v[52:55]
	v_mfma_f32_16x16x32_bf16 v[60:63], v[154:157], v[198:201], v[60:63]
	v_mfma_f32_16x16x32_bf16 v[28:31], v[146:149], v[206:209], v[28:31]
	v_mfma_f32_16x16x32_bf16 v[36:39], v[154:157], v[206:209], v[36:39]
	v_mfma_f32_16x16x32_bf16 v[12:15], v[146:149], v[214:217], v[12:15]
	v_mfma_f32_16x16x32_bf16 v[16:19], v[154:157], v[214:217], v[16:19]
	v_mfma_f32_16x16x32_bf16 v[0:3], v[146:149], v[222:225], v[0:3]
	v_mfma_f32_16x16x32_bf16 v[4:7], v[154:157], v[222:225], v[4:7]
	v_mfma_f32_16x16x32_bf16 v[52:55], v[150:153], v[202:205], v[52:55]
	v_mfma_f32_16x16x32_bf16 v[60:63], v[158:161], v[202:205], v[60:63]
	v_mfma_f32_16x16x32_bf16 v[28:31], v[150:153], v[210:213], v[28:31]
	v_mfma_f32_16x16x32_bf16 v[36:39], v[158:161], v[210:213], v[36:39]
	v_mfma_f32_16x16x32_bf16 v[12:15], v[150:153], v[218:221], v[12:15]
	v_mfma_f32_16x16x32_bf16 v[16:19], v[158:161], v[218:221], v[16:19]
	v_mfma_f32_16x16x32_bf16 v[0:3], v[150:153], v[226:229], v[0:3]
	v_mfma_f32_16x16x32_bf16 v[4:7], v[158:161], v[226:229], v[4:7]
	v_mfma_f32_16x16x32_bf16 v[80:83], v[162:165], v[198:201], v[80:83]
	v_mfma_f32_16x16x32_bf16 v[84:87], v[170:173], v[198:201], v[84:87]
	v_mfma_f32_16x16x32_bf16 v[48:51], v[162:165], v[206:209], v[48:51]
	v_mfma_f32_16x16x32_bf16 v[56:59], v[170:173], v[206:209], v[56:59]
	v_mfma_f32_16x16x32_bf16 v[24:27], v[162:165], v[214:217], v[24:27]
	v_mfma_f32_16x16x32_bf16 v[32:35], v[170:173], v[214:217], v[32:35]
	v_mfma_f32_16x16x32_bf16 v[8:11], v[162:165], v[222:225], v[8:11]
	v_mfma_f32_16x16x32_bf16 v[20:23], v[170:173], v[222:225], v[20:23]
	v_mfma_f32_16x16x32_bf16 v[80:83], v[166:169], v[202:205], v[80:83]
	v_mfma_f32_16x16x32_bf16 v[84:87], v[174:177], v[202:205], v[84:87]
	v_mfma_f32_16x16x32_bf16 v[48:51], v[166:169], v[210:213], v[48:51]
	v_mfma_f32_16x16x32_bf16 v[56:59], v[174:177], v[210:213], v[56:59]
	v_mfma_f32_16x16x32_bf16 v[24:27], v[166:169], v[218:221], v[24:27]
	v_mfma_f32_16x16x32_bf16 v[32:35], v[174:177], v[218:221], v[32:35]
	v_mfma_f32_16x16x32_bf16 v[8:11], v[166:169], v[226:229], v[8:11]
	v_mfma_f32_16x16x32_bf16 v[20:23], v[174:177], v[226:229], v[20:23]
	s_setprio 0
	s_barrier
	s_add_i32 s59, 0, 0x18000
	s_add_i32 s60, 0, 0x1c000
	v_add_u32_e32 v158, s59, v145
	v_add_u32_e32 v174, s60, v145
	ds_read_b128 v[146:149], v158
	ds_read_b128 v[150:153], v158 offset:1024
	ds_read_b128 v[154:157], v158 offset:2048
	ds_read_b128 v[158:161], v158 offset:3072
	ds_read_b128 v[162:165], v174
	ds_read_b128 v[166:169], v174 offset:1024
	ds_read_b128 v[170:173], v174 offset:2048
	ds_read_b128 v[174:177], v174 offset:3072
	s_add_u32 s30, s44, 0x40000
	s_addc_u32 s31, s45, 0
	s_mov_b32 m0, s46
	v_lshl_add_u64 v[244:245], s[30:31], 0, v[134:135]
	ds_read_b128 v[198:201], v141 offset:32768
	ds_read_b128 v[202:205], v141 offset:33792
	ds_read_b128 v[206:209], v141 offset:34816
	ds_read_b128 v[210:213], v141 offset:35840
	ds_read_b128 v[214:217], v141 offset:36864
	ds_read_b128 v[218:221], v141 offset:37888
	ds_read_b128 v[222:225], v141 offset:38912
	ds_read_b128 v[226:229], v141 offset:39936
	global_load_lds_dwordx4 v[244:245], off
	v_lshl_add_u64 v[244:245], s[30:31], 0, v[132:133]
	s_mov_b32 m0, s47
	s_nop 0
	global_load_lds_dwordx4 v[244:245], off
	s_waitcnt vmcnt(8)
	s_waitcnt lgkmcnt(0)
	s_barrier
	s_setprio 1
	v_mfma_f32_16x16x32_bf16 v[108:111], v[146:149], v[198:201], v[108:111]
	v_mfma_f32_16x16x32_bf16 v[116:119], v[154:157], v[198:201], v[116:119]
	v_mfma_f32_16x16x32_bf16 v[92:95], v[146:149], v[206:209], v[92:95]
	v_mfma_f32_16x16x32_bf16 v[100:103], v[154:157], v[206:209], v[100:103]
	v_mfma_f32_16x16x32_bf16 v[68:71], v[146:149], v[214:217], v[68:71]
	v_mfma_f32_16x16x32_bf16 v[76:79], v[154:157], v[214:217], v[76:79]
	v_mfma_f32_16x16x32_bf16 v[40:43], v[146:149], v[222:225], v[40:43]
	v_mfma_f32_16x16x32_bf16 v[44:47], v[154:157], v[222:225], v[44:47]
	v_mfma_f32_16x16x32_bf16 v[108:111], v[150:153], v[202:205], v[108:111]
	v_mfma_f32_16x16x32_bf16 v[116:119], v[158:161], v[202:205], v[116:119]
	v_mfma_f32_16x16x32_bf16 v[92:95], v[150:153], v[210:213], v[92:95]
	v_mfma_f32_16x16x32_bf16 v[100:103], v[158:161], v[210:213], v[100:103]
	v_mfma_f32_16x16x32_bf16 v[68:71], v[150:153], v[218:221], v[68:71]
	v_mfma_f32_16x16x32_bf16 v[76:79], v[158:161], v[218:221], v[76:79]
	v_mfma_f32_16x16x32_bf16 v[40:43], v[150:153], v[226:229], v[40:43]
	v_mfma_f32_16x16x32_bf16 v[44:47], v[158:161], v[226:229], v[44:47]
	v_mfma_f32_16x16x32_bf16 v[120:123], v[162:165], v[198:201], v[120:123]
	v_mfma_f32_16x16x32_bf16 v[124:127], v[170:173], v[198:201], v[124:127]
	v_mfma_f32_16x16x32_bf16 v[104:107], v[162:165], v[206:209], v[104:107]
	v_mfma_f32_16x16x32_bf16 v[112:115], v[170:173], v[206:209], v[112:115]
	v_mfma_f32_16x16x32_bf16 v[88:91], v[162:165], v[214:217], v[88:91]
	v_mfma_f32_16x16x32_bf16 v[96:99], v[170:173], v[214:217], v[96:99]
	v_mfma_f32_16x16x32_bf16 v[64:67], v[162:165], v[222:225], v[64:67]
	v_mfma_f32_16x16x32_bf16 v[72:75], v[170:173], v[222:225], v[72:75]
	v_mfma_f32_16x16x32_bf16 v[120:123], v[166:169], v[202:205], v[120:123]
	v_mfma_f32_16x16x32_bf16 v[124:127], v[174:177], v[202:205], v[124:127]
	v_mfma_f32_16x16x32_bf16 v[104:107], v[166:169], v[210:213], v[104:107]
	v_mfma_f32_16x16x32_bf16 v[112:115], v[174:177], v[210:213], v[112:115]
	v_mfma_f32_16x16x32_bf16 v[88:91], v[166:169], v[218:221], v[88:91]
	v_mfma_f32_16x16x32_bf16 v[96:99], v[174:177], v[218:221], v[96:99]
	v_mfma_f32_16x16x32_bf16 v[64:67], v[166:169], v[226:229], v[64:67]
	v_mfma_f32_16x16x32_bf16 v[72:75], v[174:177], v[226:229], v[72:75]
	s_setprio 0
	s_barrier
	s_add_i32 s30, s59, s4
	v_lshl_add_u64 v[142:143], v[142:143], 0, s[90:91]
	s_mov_b32 m0, s30
	ds_read_b128 v[198:201], v141 offset:49152
	ds_read_b128 v[202:205], v141 offset:50176
	ds_read_b128 v[206:209], v141 offset:51200
	ds_read_b128 v[210:213], v141 offset:52224
	ds_read_b128 v[214:217], v141 offset:53248
	ds_read_b128 v[218:221], v141 offset:54272
	ds_read_b128 v[222:225], v141 offset:55296
	ds_read_b128 v[226:229], v141 offset:56320
	global_load_lds_dwordx4 v[142:143], off
	s_add_i32 m0, s30, 0x2000
	s_add_u32 s30, s34, 0x40080
	v_lshl_add_u64 v[142:143], v[238:239], 0, s[90:91]
	s_addc_u32 s31, s35, 0
	s_add_i32 s34, s60, s4
	global_load_lds_dwordx4 v[142:143], off
	v_lshl_add_u64 v[142:143], s[30:31], 0, v[128:129]
	s_mov_b32 m0, s34
	s_nop 0
	global_load_lds_dwordx4 v[142:143], off
	v_lshl_add_u64 v[142:143], s[30:31], 0, v[130:131]
	s_add_i32 m0, s34, 0x2000
	s_nop 0
	global_load_lds_dwordx4 v[142:143], off
	v_lshl_add_u64 v[142:143], v[240:241], 0, s[90:91]
	s_mov_b32 m0, s21
	s_nop 0
	global_load_lds_dwordx4 v[142:143], off
	v_lshl_add_u64 v[142:143], v[242:243], 0, s[90:91]
	s_mov_b32 m0, s48
	s_nop 0
	global_load_lds_dwordx4 v[142:143], off
	s_waitcnt vmcnt(8)
	s_waitcnt lgkmcnt(0)
	s_barrier
	s_setprio 1
	v_mfma_f32_16x16x32_bf16 v[52:55], v[146:149], v[198:201], v[52:55]
	v_mfma_f32_16x16x32_bf16 v[60:63], v[154:157], v[198:201], v[60:63]
	v_mfma_f32_16x16x32_bf16 v[28:31], v[146:149], v[206:209], v[28:31]
	v_mfma_f32_16x16x32_bf16 v[36:39], v[154:157], v[206:209], v[36:39]
	v_mfma_f32_16x16x32_bf16 v[12:15], v[146:149], v[214:217], v[12:15]
	v_mfma_f32_16x16x32_bf16 v[16:19], v[154:157], v[214:217], v[16:19]
	v_mfma_f32_16x16x32_bf16 v[0:3], v[146:149], v[222:225], v[0:3]
	v_mfma_f32_16x16x32_bf16 v[4:7], v[154:157], v[222:225], v[4:7]
	v_mfma_f32_16x16x32_bf16 v[52:55], v[150:153], v[202:205], v[52:55]
	v_mfma_f32_16x16x32_bf16 v[60:63], v[158:161], v[202:205], v[60:63]
	v_mfma_f32_16x16x32_bf16 v[28:31], v[150:153], v[210:213], v[28:31]
	v_mfma_f32_16x16x32_bf16 v[36:39], v[158:161], v[210:213], v[36:39]
	v_mfma_f32_16x16x32_bf16 v[12:15], v[150:153], v[218:221], v[12:15]
	v_mfma_f32_16x16x32_bf16 v[16:19], v[158:161], v[218:221], v[16:19]
	v_mfma_f32_16x16x32_bf16 v[0:3], v[150:153], v[226:229], v[0:3]
	v_mfma_f32_16x16x32_bf16 v[4:7], v[158:161], v[226:229], v[4:7]
	v_mfma_f32_16x16x32_bf16 v[80:83], v[162:165], v[198:201], v[80:83]
	v_mfma_f32_16x16x32_bf16 v[84:87], v[170:173], v[198:201], v[84:87]
	v_mfma_f32_16x16x32_bf16 v[48:51], v[162:165], v[206:209], v[48:51]
	v_mfma_f32_16x16x32_bf16 v[56:59], v[170:173], v[206:209], v[56:59]
	v_mfma_f32_16x16x32_bf16 v[24:27], v[162:165], v[214:217], v[24:27]
	v_mfma_f32_16x16x32_bf16 v[32:35], v[170:173], v[214:217], v[32:35]
	v_mfma_f32_16x16x32_bf16 v[8:11], v[162:165], v[222:225], v[8:11]
	v_mfma_f32_16x16x32_bf16 v[20:23], v[170:173], v[222:225], v[20:23]
	v_mfma_f32_16x16x32_bf16 v[80:83], v[166:169], v[202:205], v[80:83]
	v_mfma_f32_16x16x32_bf16 v[84:87], v[174:177], v[202:205], v[84:87]
	v_mfma_f32_16x16x32_bf16 v[48:51], v[166:169], v[210:213], v[48:51]
	v_mfma_f32_16x16x32_bf16 v[56:59], v[174:177], v[210:213], v[56:59]
	v_mfma_f32_16x16x32_bf16 v[24:27], v[166:169], v[218:221], v[24:27]
	v_mfma_f32_16x16x32_bf16 v[32:35], v[174:177], v[218:221], v[32:35]
	v_mfma_f32_16x16x32_bf16 v[8:11], v[166:169], v[226:229], v[8:11]
	v_mfma_f32_16x16x32_bf16 v[20:23], v[174:177], v[226:229], v[20:23]
	s_setprio 0
	s_barrier
	s_add_i32 s58, s58, 2
	s_add_u32 s56, s56, 0x100
	s_addc_u32 s57, s57, 0
	s_add_u32 s28, s28, 0x100
	s_addc_u32 s29, s29, 0
	s_cmp_gt_u32 s58, 13
	s_cbranch_scc0 .LBB0_273
	s_and_b64 vcc, exec, s[16:17]
	s_cbranch_vccz .LBB0_276
	s_barrier

.LBB0_296:
	s_add_u32 s8, s10, 0x100
	s_addc_u32 s9, s11, 0
	s_add_i32 s30, 0, 0x10000
	s_cmp_eq_u32 s55, 2
	s_cselect_b32 s37, s27, s9
	s_cselect_b32 s36, s26, s8
	v_add_u32_e32 v138, s30, v141
	s_cselect_b32 s35, s29, s53
	s_cselect_b32 s34, s28, s52
	s_add_i32 s31, 0, 0x14000
	ds_read_b128 v[148:151], v138
	ds_read_b128 v[152:155], v138 offset:1024
	ds_read_b128 v[156:159], v138 offset:2048
	ds_read_b128 v[160:163], v138 offset:3072
	v_add_u32_e32 v138, s31, v141
	ds_read_b128 v[164:167], v138
	ds_read_b128 v[168:171], v138 offset:1024
	ds_read_b128 v[172:175], v138 offset:2048
	ds_read_b128 v[198:201], v138 offset:3072
	v_lshl_add_u64 v[138:139], s[10:11], 0, v[136:137]
	s_add_i32 m0, s39, 0xc000
	ds_read_b128 v[202:205], v145
	ds_read_b128 v[206:209], v145 offset:1024
	ds_read_b128 v[210:213], v145 offset:2048
	ds_read_b128 v[214:217], v145 offset:3072
	ds_read_b128 v[218:221], v145 offset:4096
	ds_read_b128 v[222:225], v145 offset:5120
	ds_read_b128 v[226:229], v145 offset:6144
	ds_read_b128 v[238:241], v145 offset:7168
	global_load_lds_dwordx4 v[138:139], off
	v_lshl_add_u64 v[138:139], s[10:11], 0, v[134:135]
	s_add_i32 m0, s39, 0xe000
	s_nop 0
	global_load_lds_dwordx4 v[138:139], off
	s_waitcnt vmcnt(8)
	s_waitcnt lgkmcnt(0)
	s_barrier
	s_setprio 1
	v_mfma_f32_16x16x32_bf16 v[124:127], v[148:151], v[202:205], v[124:127]
	v_mfma_f32_16x16x32_bf16 v[120:123], v[156:159], v[202:205], v[120:123]
	v_mfma_f32_16x16x32_bf16 v[116:119], v[148:151], v[210:213], v[116:119]
	v_mfma_f32_16x16x32_bf16 v[112:115], v[156:159], v[210:213], v[112:115]
	v_mfma_f32_16x16x32_bf16 v[108:111], v[148:151], v[218:221], v[108:111]
	v_mfma_f32_16x16x32_bf16 v[104:107], v[156:159], v[218:221], v[104:107]
	v_mfma_f32_16x16x32_bf16 v[100:103], v[148:151], v[226:229], v[100:103]
	v_mfma_f32_16x16x32_bf16 v[96:99], v[156:159], v[226:229], v[96:99]
	v_mfma_f32_16x16x32_bf16 v[124:127], v[152:155], v[206:209], v[124:127]
	v_mfma_f32_16x16x32_bf16 v[120:123], v[160:163], v[206:209], v[120:123]
	v_mfma_f32_16x16x32_bf16 v[116:119], v[152:155], v[214:217], v[116:119]
	v_mfma_f32_16x16x32_bf16 v[112:115], v[160:163], v[214:217], v[112:115]
	v_mfma_f32_16x16x32_bf16 v[108:111], v[152:155], v[222:225], v[108:111]
	v_mfma_f32_16x16x32_bf16 v[104:107], v[160:163], v[222:225], v[104:107]
	v_mfma_f32_16x16x32_bf16 v[100:103], v[152:155], v[238:241], v[100:103]
	v_mfma_f32_16x16x32_bf16 v[96:99], v[160:163], v[238:241], v[96:99]
	v_mfma_f32_16x16x32_bf16 v[60:63], v[164:167], v[202:205], v[60:63]
	v_mfma_f32_16x16x32_bf16 v[56:59], v[172:175], v[202:205], v[56:59]
	v_mfma_f32_16x16x32_bf16 v[52:55], v[164:167], v[210:213], v[52:55]
	v_mfma_f32_16x16x32_bf16 v[48:51], v[172:175], v[210:213], v[48:51]
	v_mfma_f32_16x16x32_bf16 v[44:47], v[164:167], v[218:221], v[44:47]
	v_mfma_f32_16x16x32_bf16 v[40:43], v[172:175], v[218:221], v[40:43]
	v_mfma_f32_16x16x32_bf16 v[36:39], v[164:167], v[226:229], v[36:39]
	v_mfma_f32_16x16x32_bf16 v[32:35], v[172:175], v[226:229], v[32:35]
	v_mfma_f32_16x16x32_bf16 v[60:63], v[168:171], v[206:209], v[60:63]
	v_mfma_f32_16x16x32_bf16 v[56:59], v[198:201], v[206:209], v[56:59]
	v_mfma_f32_16x16x32_bf16 v[52:55], v[168:171], v[214:217], v[52:55]
	v_mfma_f32_16x16x32_bf16 v[48:51], v[198:201], v[214:217], v[48:51]
	v_mfma_f32_16x16x32_bf16 v[44:47], v[168:171], v[222:225], v[44:47]
	v_mfma_f32_16x16x32_bf16 v[40:43], v[198:201], v[222:225], v[40:43]
	v_mfma_f32_16x16x32_bf16 v[36:39], v[168:171], v[238:241], v[36:39]
	v_mfma_f32_16x16x32_bf16 v[32:35], v[198:201], v[238:241], v[32:35]
	s_setprio 0
	s_barrier
	s_add_i32 s10, s30, s38
	v_lshl_add_u64 v[138:139], s[34:35], 0, v[130:131]
	s_mov_b32 m0, s10
	ds_read_b128 v[202:205], v145 offset:16384
	ds_read_b128 v[206:209], v145 offset:17408
	ds_read_b128 v[210:213], v145 offset:18432
	ds_read_b128 v[214:217], v145 offset:19456
	ds_read_b128 v[218:221], v145 offset:20480
	ds_read_b128 v[222:225], v145 offset:21504
	ds_read_b128 v[226:229], v145 offset:22528
	ds_read_b128 v[238:241], v145 offset:23552
	global_load_lds_dwordx4 v[138:139], off
	s_add_i32 m0, s10, 0x2000
	s_add_u32 s10, s34, 0x18000
	v_lshl_add_u64 v[176:177], s[34:35], 0, v[132:133]
	s_addc_u32 s11, s35, 0
	s_add_i32 s30, s31, s38
	global_load_lds_dwordx4 v[176:177], off
	v_lshl_add_u64 v[242:243], s[10:11], 0, v[130:131]
	s_mov_b32 m0, s30
	v_lshl_add_u64 v[244:245], s[36:37], 0, v[132:133]
	global_load_lds_dwordx4 v[242:243], off
	v_lshl_add_u64 v[242:243], s[10:11], 0, v[132:133]
	s_add_i32 m0, s30, 0x2000
	s_nop 0
	global_load_lds_dwordx4 v[242:243], off
	v_lshl_add_u64 v[242:243], s[36:37], 0, v[130:131]
	s_mov_b32 m0, s39
	s_nop 0
	global_load_lds_dwordx4 v[242:243], off
	s_mov_b32 m0, s40
	s_nop 0
	global_load_lds_dwordx4 v[244:245], off
	s_waitcnt vmcnt(8)
	s_waitcnt lgkmcnt(0)
	s_barrier
	s_setprio 1
	v_mfma_f32_16x16x32_bf16 v[92:95], v[148:151], v[202:205], v[92:95]
	v_mfma_f32_16x16x32_bf16 v[88:91], v[156:159], v[202:205], v[88:91]
	v_mfma_f32_16x16x32_bf16 v[84:87], v[148:151], v[210:213], v[84:87]
	v_mfma_f32_16x16x32_bf16 v[80:83], v[156:159], v[210:213], v[80:83]
	v_mfma_f32_16x16x32_bf16 v[76:79], v[148:151], v[218:221], v[76:79]
	v_mfma_f32_16x16x32_bf16 v[72:75], v[156:159], v[218:221], v[72:75]
	v_mfma_f32_16x16x32_bf16 v[68:71], v[148:151], v[226:229], v[68:71]
	v_mfma_f32_16x16x32_bf16 v[64:67], v[156:159], v[226:229], v[64:67]
	v_mfma_f32_16x16x32_bf16 v[92:95], v[152:155], v[206:209], v[92:95]
	v_mfma_f32_16x16x32_bf16 v[88:91], v[160:163], v[206:209], v[88:91]
	v_mfma_f32_16x16x32_bf16 v[84:87], v[152:155], v[214:217], v[84:87]
	v_mfma_f32_16x16x32_bf16 v[80:83], v[160:163], v[214:217], v[80:83]
	v_mfma_f32_16x16x32_bf16 v[76:79], v[152:155], v[222:225], v[76:79]
	v_mfma_f32_16x16x32_bf16 v[72:75], v[160:163], v[222:225], v[72:75]
	v_mfma_f32_16x16x32_bf16 v[68:71], v[152:155], v[238:241], v[68:71]
	v_mfma_f32_16x16x32_bf16 v[64:67], v[160:163], v[238:241], v[64:67]
	v_mfma_f32_16x16x32_bf16 v[28:31], v[164:167], v[202:205], v[28:31]
	v_mfma_f32_16x16x32_bf16 v[24:27], v[172:175], v[202:205], v[24:27]
	v_mfma_f32_16x16x32_bf16 v[20:23], v[164:167], v[210:213], v[20:23]
	v_mfma_f32_16x16x32_bf16 v[16:19], v[172:175], v[210:213], v[16:19]
	v_mfma_f32_16x16x32_bf16 v[12:15], v[164:167], v[218:221], v[12:15]
	v_mfma_f32_16x16x32_bf16 v[8:11], v[172:175], v[218:221], v[8:11]
	v_mfma_f32_16x16x32_bf16 v[4:7], v[164:167], v[226:229], v[4:7]
	v_mfma_f32_16x16x32_bf16 v[0:3], v[172:175], v[226:229], v[0:3]
	v_mfma_f32_16x16x32_bf16 v[28:31], v[168:171], v[206:209], v[28:31]
	v_mfma_f32_16x16x32_bf16 v[24:27], v[198:201], v[206:209], v[24:27]
	v_mfma_f32_16x16x32_bf16 v[20:23], v[168:171], v[214:217], v[20:23]
	v_mfma_f32_16x16x32_bf16 v[16:19], v[198:201], v[214:217], v[16:19]
	v_mfma_f32_16x16x32_bf16 v[12:15], v[168:171], v[222:225], v[12:15]
	v_mfma_f32_16x16x32_bf16 v[8:11], v[198:201], v[222:225], v[8:11]
	v_mfma_f32_16x16x32_bf16 v[4:7], v[168:171], v[238:241], v[4:7]
	v_mfma_f32_16x16x32_bf16 v[0:3], v[198:201], v[238:241], v[0:3]
	s_setprio 0
	s_barrier
	s_add_i32 s30, 0, 0x18000
	v_add_u32_e32 v147, s30, v141
	s_add_i32 s31, 0, 0x1c000
	ds_read_b128 v[148:151], v147
	ds_read_b128 v[152:155], v147 offset:1024
	ds_read_b128 v[156:159], v147 offset:2048
	ds_read_b128 v[160:163], v147 offset:3072
	v_add_u32_e32 v147, s31, v141
	ds_read_b128 v[164:167], v147
	ds_read_b128 v[168:171], v147 offset:1024
	ds_read_b128 v[172:175], v147 offset:2048
	ds_read_b128 v[198:201], v147 offset:3072
	s_add_u32 s10, s36, 0x18000
	s_addc_u32 s11, s37, 0
	s_mov_b32 m0, s41
	v_lshl_add_u64 v[246:247], s[10:11], 0, v[130:131]
	ds_read_b128 v[202:205], v145 offset:32768
	ds_read_b128 v[206:209], v145 offset:33792
	ds_read_b128 v[210:213], v145 offset:34816
	ds_read_b128 v[214:217], v145 offset:35840
	ds_read_b128 v[218:221], v145 offset:36864
	ds_read_b128 v[222:225], v145 offset:37888
	ds_read_b128 v[226:229], v145 offset:38912
	ds_read_b128 v[238:241], v145 offset:39936
	global_load_lds_dwordx4 v[246:247], off
	v_lshl_add_u64 v[246:247], s[10:11], 0, v[132:133]
	s_mov_b32 m0, s42
	s_nop 0
	global_load_lds_dwordx4 v[246:247], off
	s_waitcnt vmcnt(8)
	s_waitcnt lgkmcnt(0)
	s_barrier
	s_setprio 1
	v_mfma_f32_16x16x32_bf16 v[124:127], v[148:151], v[202:205], v[124:127]
	v_mfma_f32_16x16x32_bf16 v[120:123], v[156:159], v[202:205], v[120:123]
	v_mfma_f32_16x16x32_bf16 v[116:119], v[148:151], v[210:213], v[116:119]
	v_mfma_f32_16x16x32_bf16 v[112:115], v[156:159], v[210:213], v[112:115]
	v_mfma_f32_16x16x32_bf16 v[108:111], v[148:151], v[218:221], v[108:111]
	v_mfma_f32_16x16x32_bf16 v[104:107], v[156:159], v[218:221], v[104:107]
	v_mfma_f32_16x16x32_bf16 v[100:103], v[148:151], v[226:229], v[100:103]
	v_mfma_f32_16x16x32_bf16 v[96:99], v[156:159], v[226:229], v[96:99]
	v_mfma_f32_16x16x32_bf16 v[124:127], v[152:155], v[206:209], v[124:127]
	v_mfma_f32_16x16x32_bf16 v[120:123], v[160:163], v[206:209], v[120:123]
	v_mfma_f32_16x16x32_bf16 v[116:119], v[152:155], v[214:217], v[116:119]
	v_mfma_f32_16x16x32_bf16 v[112:115], v[160:163], v[214:217], v[112:115]
	v_mfma_f32_16x16x32_bf16 v[108:111], v[152:155], v[222:225], v[108:111]
	v_mfma_f32_16x16x32_bf16 v[104:107], v[160:163], v[222:225], v[104:107]
	v_mfma_f32_16x16x32_bf16 v[100:103], v[152:155], v[238:241], v[100:103]
	v_mfma_f32_16x16x32_bf16 v[96:99], v[160:163], v[238:241], v[96:99]
	v_mfma_f32_16x16x32_bf16 v[60:63], v[164:167], v[202:205], v[60:63]
	v_mfma_f32_16x16x32_bf16 v[56:59], v[172:175], v[202:205], v[56:59]
	v_mfma_f32_16x16x32_bf16 v[52:55], v[164:167], v[210:213], v[52:55]
	v_mfma_f32_16x16x32_bf16 v[48:51], v[172:175], v[210:213], v[48:51]
	v_mfma_f32_16x16x32_bf16 v[44:47], v[164:167], v[218:221], v[44:47]
	v_mfma_f32_16x16x32_bf16 v[40:43], v[172:175], v[218:221], v[40:43]
	v_mfma_f32_16x16x32_bf16 v[36:39], v[164:167], v[226:229], v[36:39]
	v_mfma_f32_16x16x32_bf16 v[32:35], v[172:175], v[226:229], v[32:35]
	v_mfma_f32_16x16x32_bf16 v[60:63], v[168:171], v[206:209], v[60:63]
	v_mfma_f32_16x16x32_bf16 v[56:59], v[198:201], v[206:209], v[56:59]
	v_mfma_f32_16x16x32_bf16 v[52:55], v[168:171], v[214:217], v[52:55]
	v_mfma_f32_16x16x32_bf16 v[48:51], v[198:201], v[214:217], v[48:51]
	v_mfma_f32_16x16x32_bf16 v[44:47], v[168:171], v[222:225], v[44:47]
	v_mfma_f32_16x16x32_bf16 v[40:43], v[198:201], v[222:225], v[40:43]
	v_mfma_f32_16x16x32_bf16 v[36:39], v[168:171], v[238:241], v[36:39]
	v_mfma_f32_16x16x32_bf16 v[32:35], v[198:201], v[238:241], v[32:35]
	s_setprio 0
	s_barrier
	s_add_i32 s10, s30, s38
	v_lshl_add_u64 v[138:139], v[138:139], 0, s[90:91]
	s_mov_b32 m0, s10
	ds_read_b128 v[202:205], v145 offset:49152
	ds_read_b128 v[206:209], v145 offset:50176
	ds_read_b128 v[210:213], v145 offset:51200
	ds_read_b128 v[214:217], v145 offset:52224
	ds_read_b128 v[218:221], v145 offset:53248
	ds_read_b128 v[222:225], v145 offset:54272
	ds_read_b128 v[226:229], v145 offset:55296
	ds_read_b128 v[238:241], v145 offset:56320
	global_load_lds_dwordx4 v[138:139], off
	s_add_i32 m0, s10, 0x2000
	s_add_u32 s10, s34, 0x18080
	v_lshl_add_u64 v[138:139], v[176:177], 0, s[90:91]
	s_addc_u32 s11, s35, 0
	s_add_i32 s30, s31, s38
	global_load_lds_dwordx4 v[138:139], off
	v_lshl_add_u64 v[138:139], s[10:11], 0, v[130:131]
	s_mov_b32 m0, s30
	s_nop 0
	global_load_lds_dwordx4 v[138:139], off
	v_lshl_add_u64 v[138:139], s[10:11], 0, v[132:133]
	s_add_i32 m0, s30, 0x2000
	s_nop 0
	global_load_lds_dwordx4 v[138:139], off
	v_lshl_add_u64 v[138:139], v[242:243], 0, s[90:91]
	s_mov_b32 m0, s45
	s_nop 0
	global_load_lds_dwordx4 v[138:139], off
	v_lshl_add_u64 v[138:139], v[244:245], 0, s[90:91]
	s_mov_b32 m0, s46
	s_nop 0
	global_load_lds_dwordx4 v[138:139], off
	s_waitcnt vmcnt(8)
	s_waitcnt lgkmcnt(0)
	s_barrier
	s_setprio 1
	v_mfma_f32_16x16x32_bf16 v[92:95], v[148:151], v[202:205], v[92:95]
	v_mfma_f32_16x16x32_bf16 v[88:91], v[156:159], v[202:205], v[88:91]
	v_mfma_f32_16x16x32_bf16 v[84:87], v[148:151], v[210:213], v[84:87]
	v_mfma_f32_16x16x32_bf16 v[80:83], v[156:159], v[210:213], v[80:83]
	v_mfma_f32_16x16x32_bf16 v[76:79], v[148:151], v[218:221], v[76:79]
	v_mfma_f32_16x16x32_bf16 v[72:75], v[156:159], v[218:221], v[72:75]
	v_mfma_f32_16x16x32_bf16 v[68:71], v[148:151], v[226:229], v[68:71]
	v_mfma_f32_16x16x32_bf16 v[64:67], v[156:159], v[226:229], v[64:67]
	v_mfma_f32_16x16x32_bf16 v[92:95], v[152:155], v[206:209], v[92:95]
	v_mfma_f32_16x16x32_bf16 v[88:91], v[160:163], v[206:209], v[88:91]
	v_mfma_f32_16x16x32_bf16 v[84:87], v[152:155], v[214:217], v[84:87]
	v_mfma_f32_16x16x32_bf16 v[80:83], v[160:163], v[214:217], v[80:83]
	v_mfma_f32_16x16x32_bf16 v[76:79], v[152:155], v[222:225], v[76:79]
	v_mfma_f32_16x16x32_bf16 v[72:75], v[160:163], v[222:225], v[72:75]
	v_mfma_f32_16x16x32_bf16 v[68:71], v[152:155], v[238:241], v[68:71]
	v_mfma_f32_16x16x32_bf16 v[64:67], v[160:163], v[238:241], v[64:67]
	v_mfma_f32_16x16x32_bf16 v[28:31], v[164:167], v[202:205], v[28:31]
	v_mfma_f32_16x16x32_bf16 v[24:27], v[172:175], v[202:205], v[24:27]
	v_mfma_f32_16x16x32_bf16 v[20:23], v[164:167], v[210:213], v[20:23]
	v_mfma_f32_16x16x32_bf16 v[16:19], v[172:175], v[210:213], v[16:19]
	v_mfma_f32_16x16x32_bf16 v[12:15], v[164:167], v[218:221], v[12:15]
	v_mfma_f32_16x16x32_bf16 v[8:11], v[172:175], v[218:221], v[8:11]
	v_mfma_f32_16x16x32_bf16 v[4:7], v[164:167], v[226:229], v[4:7]
	v_mfma_f32_16x16x32_bf16 v[0:3], v[172:175], v[226:229], v[0:3]
	v_mfma_f32_16x16x32_bf16 v[28:31], v[168:171], v[206:209], v[28:31]
	v_mfma_f32_16x16x32_bf16 v[24:27], v[198:201], v[206:209], v[24:27]
	v_mfma_f32_16x16x32_bf16 v[20:23], v[168:171], v[214:217], v[20:23]
	v_mfma_f32_16x16x32_bf16 v[16:19], v[198:201], v[214:217], v[16:19]
	v_mfma_f32_16x16x32_bf16 v[12:15], v[168:171], v[222:225], v[12:15]
	v_mfma_f32_16x16x32_bf16 v[8:11], v[198:201], v[222:225], v[8:11]
	v_mfma_f32_16x16x32_bf16 v[4:7], v[168:171], v[238:241], v[4:7]
	v_mfma_f32_16x16x32_bf16 v[0:3], v[198:201], v[238:241], v[0:3]
	s_setprio 0
	s_barrier
	s_add_i32 s55, s55, 2
	s_add_u32 s52, s52, 0x100
	s_addc_u32 s53, s53, 0
	s_cmp_gt_u32 s55, 3
	s_mov_b64 s[10:11], s[8:9]
	s_cbranch_scc0 .LBB0_296
	s_and_b64 vcc, exec, s[24:25]
	s_cbranch_vccz .LBB0_299
	s_barrier

.LBB0_344:
	s_add_u32 s47, s34, s46
	s_addc_u32 s59, s35, 0
	s_add_u32 s48, s47, 0x100
	s_addc_u32 s49, s59, 0
	s_and_b64 s[30:31], s[44:45], exec
	s_cselect_b32 s49, s19, s49
	s_cselect_b32 s48, s57, s48
	s_add_u32 s30, s36, s46
	s_addc_u32 s31, s37, 0
	s_add_u32 s46, s30, 0x100
	s_addc_u32 s50, s31, 0
	s_add_i32 s74, 0, 0x10000
	s_and_b64 s[30:31], s[44:45], exec
	s_cselect_b32 s51, s17, s50
	s_cselect_b32 s50, s58, s46
	s_add_i32 s45, 0, 0x14000
	s_add_u32 s30, s47, 0x10080
	s_addc_u32 s31, s59, 0
	s_add_i32 s83, s74, s40
	s_add_i32 m0, s20, 0xc000
	s_add_i32 s82, s20, 0xe000
	s_add_i32 s84, s83, 0x2000
	s_add_u32 s60, s50, 0x10000
	v_add_u32_e32 v152, s74, v137
	v_add_u32_e32 v168, s45, v137
	s_addc_u32 s61, s51, 0
	s_add_i32 s85, s45, s40
	ds_read_b128 v[140:143], v152
	ds_read_b128 v[144:147], v152 offset:1024
	ds_read_b128 v[148:151], v152 offset:2048
	ds_read_b128 v[152:155], v152 offset:3072
	ds_read_b128 v[156:159], v168
	ds_read_b128 v[160:163], v168 offset:1024
	ds_read_b128 v[164:167], v168 offset:2048
	ds_read_b128 v[168:171], v168 offset:3072
	s_add_i32 s86, s85, 0x2000
	s_add_i32 s87, 0, 0x18000
	s_add_i32 s88, 0, 0x1c000
	s_add_u32 s46, s48, 0x10000
	s_addc_u32 s47, s49, 0
	s_add_i32 s73, s87, s40
	s_add_i32 s59, s73, 0x2000
	s_add_u32 s44, s50, 0x10080
	s_addc_u32 s45, s51, 0
	s_add_i32 s81, s88, s40
	s_add_i32 s74, s81, 0x2000
	v_lshl_add_u64 v[176:177], s[30:31], 0, v[134:135]
	ds_read_b128 v[172:175], v139
	ds_read_b128 v[198:201], v139 offset:1024
	ds_read_b128 v[202:205], v139 offset:2048
	ds_read_b128 v[206:209], v139 offset:3072
	ds_read_b128 v[210:213], v139 offset:4096
	ds_read_b128 v[214:217], v139 offset:5120
	ds_read_b128 v[218:221], v139 offset:6144
	ds_read_b128 v[222:225], v139 offset:7168
	global_load_lds_dwordx4 v[176:177], off
	v_lshl_add_u64 v[176:177], s[30:31], 0, v[132:133]
	s_mov_b32 m0, s82
	s_nop 0
	global_load_lds_dwordx4 v[176:177], off
	s_waitcnt vmcnt(8)
	s_waitcnt lgkmcnt(0)
	s_barrier
	s_setprio 1
	v_mfma_f32_16x16x32_bf16 v[112:115], v[140:143], v[172:175], v[112:115]
	v_mfma_f32_16x16x32_bf16 v[116:119], v[148:151], v[172:175], v[116:119]
	v_mfma_f32_16x16x32_bf16 v[96:99], v[140:143], v[202:205], v[96:99]
	v_mfma_f32_16x16x32_bf16 v[100:103], v[148:151], v[202:205], v[100:103]
	v_mfma_f32_16x16x32_bf16 v[72:75], v[140:143], v[210:213], v[72:75]
	v_mfma_f32_16x16x32_bf16 v[80:83], v[148:151], v[210:213], v[80:83]
	v_mfma_f32_16x16x32_bf16 v[40:43], v[140:143], v[218:221], v[40:43]
	v_mfma_f32_16x16x32_bf16 v[48:51], v[148:151], v[218:221], v[48:51]
	v_mfma_f32_16x16x32_bf16 v[112:115], v[144:147], v[198:201], v[112:115]
	v_mfma_f32_16x16x32_bf16 v[116:119], v[152:155], v[198:201], v[116:119]
	v_mfma_f32_16x16x32_bf16 v[96:99], v[144:147], v[206:209], v[96:99]
	v_mfma_f32_16x16x32_bf16 v[100:103], v[152:155], v[206:209], v[100:103]
	v_mfma_f32_16x16x32_bf16 v[72:75], v[144:147], v[214:217], v[72:75]
	v_mfma_f32_16x16x32_bf16 v[80:83], v[152:155], v[214:217], v[80:83]
	v_mfma_f32_16x16x32_bf16 v[40:43], v[144:147], v[222:225], v[40:43]
	v_mfma_f32_16x16x32_bf16 v[48:51], v[152:155], v[222:225], v[48:51]
	v_mfma_f32_16x16x32_bf16 v[120:123], v[156:159], v[172:175], v[120:123]
	v_mfma_f32_16x16x32_bf16 v[124:127], v[164:167], v[172:175], v[124:127]
	v_mfma_f32_16x16x32_bf16 v[104:107], v[156:159], v[202:205], v[104:107]
	v_mfma_f32_16x16x32_bf16 v[108:111], v[164:167], v[202:205], v[108:111]
	v_mfma_f32_16x16x32_bf16 v[88:91], v[156:159], v[210:213], v[88:91]
	v_mfma_f32_16x16x32_bf16 v[92:95], v[164:167], v[210:213], v[92:95]
	v_mfma_f32_16x16x32_bf16 v[64:67], v[156:159], v[218:221], v[64:67]
	v_mfma_f32_16x16x32_bf16 v[68:71], v[164:167], v[218:221], v[68:71]
	v_mfma_f32_16x16x32_bf16 v[120:123], v[160:163], v[198:201], v[120:123]
	v_mfma_f32_16x16x32_bf16 v[124:127], v[168:171], v[198:201], v[124:127]
	v_mfma_f32_16x16x32_bf16 v[104:107], v[160:163], v[206:209], v[104:107]
	v_mfma_f32_16x16x32_bf16 v[108:111], v[168:171], v[206:209], v[108:111]
	v_mfma_f32_16x16x32_bf16 v[88:91], v[160:163], v[214:217], v[88:91]
	v_mfma_f32_16x16x32_bf16 v[92:95], v[168:171], v[214:217], v[92:95]
	v_mfma_f32_16x16x32_bf16 v[64:67], v[160:163], v[222:225], v[64:67]
	v_mfma_f32_16x16x32_bf16 v[68:71], v[168:171], v[222:225], v[68:71]
	s_setprio 0
	s_barrier
	s_mov_b32 m0, s83
	v_lshl_add_u64 v[176:177], s[50:51], 0, v[128:129]
	ds_read_b128 v[172:175], v139 offset:16384
	ds_read_b128 v[198:201], v139 offset:17408
	ds_read_b128 v[202:205], v139 offset:18432
	ds_read_b128 v[206:209], v139 offset:19456
	ds_read_b128 v[210:213], v139 offset:20480
	ds_read_b128 v[214:217], v139 offset:21504
	ds_read_b128 v[218:221], v139 offset:22528
	ds_read_b128 v[222:225], v139 offset:23552
	global_load_lds_dwordx4 v[176:177], off
	v_lshl_add_u64 v[226:227], s[50:51], 0, v[130:131]
	s_mov_b32 m0, s84
	v_lshl_add_u64 v[228:229], s[60:61], 0, v[128:129]
	global_load_lds_dwordx4 v[226:227], off
	s_mov_b32 m0, s85
	v_lshl_add_u64 v[238:239], s[48:49], 0, v[132:133]
	global_load_lds_dwordx4 v[228:229], off
	v_lshl_add_u64 v[228:229], s[60:61], 0, v[130:131]
	s_mov_b32 m0, s86
	s_nop 0
	global_load_lds_dwordx4 v[228:229], off
	v_lshl_add_u64 v[228:229], s[48:49], 0, v[134:135]
	s_mov_b32 m0, s20
	s_nop 0
	global_load_lds_dwordx4 v[228:229], off
	s_mov_b32 m0, s21
	s_nop 0
	global_load_lds_dwordx4 v[238:239], off
	s_waitcnt vmcnt(8)
	s_waitcnt lgkmcnt(0)
	s_barrier
	s_setprio 1
	v_mfma_f32_16x16x32_bf16 v[56:59], v[140:143], v[172:175], v[56:59]
	v_mfma_f32_16x16x32_bf16 v[60:63], v[148:151], v[172:175], v[60:63]
	v_mfma_f32_16x16x32_bf16 v[32:35], v[140:143], v[202:205], v[32:35]
	v_mfma_f32_16x16x32_bf16 v[36:39], v[148:151], v[202:205], v[36:39]
	v_mfma_f32_16x16x32_bf16 v[16:19], v[140:143], v[210:213], v[16:19]
	v_mfma_f32_16x16x32_bf16 v[20:23], v[148:151], v[210:213], v[20:23]
	v_mfma_f32_16x16x32_bf16 v[0:3], v[140:143], v[218:221], v[0:3]
	v_mfma_f32_16x16x32_bf16 v[4:7], v[148:151], v[218:221], v[4:7]
	v_mfma_f32_16x16x32_bf16 v[56:59], v[144:147], v[198:201], v[56:59]
	v_mfma_f32_16x16x32_bf16 v[60:63], v[152:155], v[198:201], v[60:63]
	v_mfma_f32_16x16x32_bf16 v[32:35], v[144:147], v[206:209], v[32:35]
	v_mfma_f32_16x16x32_bf16 v[36:39], v[152:155], v[206:209], v[36:39]
	v_mfma_f32_16x16x32_bf16 v[16:19], v[144:147], v[214:217], v[16:19]
	v_mfma_f32_16x16x32_bf16 v[20:23], v[152:155], v[214:217], v[20:23]
	v_mfma_f32_16x16x32_bf16 v[0:3], v[144:147], v[222:225], v[0:3]
	v_mfma_f32_16x16x32_bf16 v[4:7], v[152:155], v[222:225], v[4:7]
	v_mfma_f32_16x16x32_bf16 v[76:79], v[156:159], v[172:175], v[76:79]
	v_mfma_f32_16x16x32_bf16 v[84:87], v[164:167], v[172:175], v[84:87]
	v_mfma_f32_16x16x32_bf16 v[44:47], v[156:159], v[202:205], v[44:47]
	v_mfma_f32_16x16x32_bf16 v[52:55], v[164:167], v[202:205], v[52:55]
	v_mfma_f32_16x16x32_bf16 v[24:27], v[156:159], v[210:213], v[24:27]
	v_mfma_f32_16x16x32_bf16 v[28:31], v[164:167], v[210:213], v[28:31]
	v_mfma_f32_16x16x32_bf16 v[8:11], v[156:159], v[218:221], v[8:11]
	v_mfma_f32_16x16x32_bf16 v[12:15], v[164:167], v[218:221], v[12:15]
	v_mfma_f32_16x16x32_bf16 v[76:79], v[160:163], v[198:201], v[76:79]
	v_mfma_f32_16x16x32_bf16 v[84:87], v[168:171], v[198:201], v[84:87]
	v_mfma_f32_16x16x32_bf16 v[44:47], v[160:163], v[206:209], v[44:47]
	v_mfma_f32_16x16x32_bf16 v[52:55], v[168:171], v[206:209], v[52:55]
	v_mfma_f32_16x16x32_bf16 v[24:27], v[160:163], v[214:217], v[24:27]
	v_mfma_f32_16x16x32_bf16 v[28:31], v[168:171], v[214:217], v[28:31]
	v_mfma_f32_16x16x32_bf16 v[8:11], v[160:163], v[222:225], v[8:11]
	v_mfma_f32_16x16x32_bf16 v[12:15], v[168:171], v[222:225], v[12:15]
	s_setprio 0
	s_barrier
	v_add_u32_e32 v152, s87, v137
	v_add_u32_e32 v168, s88, v137
	ds_read_b128 v[140:143], v152
	ds_read_b128 v[144:147], v152 offset:1024
	ds_read_b128 v[148:151], v152 offset:2048
	ds_read_b128 v[152:155], v152 offset:3072
	ds_read_b128 v[156:159], v168
	ds_read_b128 v[160:163], v168 offset:1024
	ds_read_b128 v[164:167], v168 offset:2048
	ds_read_b128 v[168:171], v168 offset:3072
	s_mov_b32 m0, s25
	v_lshl_add_u64 v[240:241], s[46:47], 0, v[134:135]
	ds_read_b128 v[172:175], v139 offset:32768
	ds_read_b128 v[198:201], v139 offset:33792
	ds_read_b128 v[202:205], v139 offset:34816
	ds_read_b128 v[206:209], v139 offset:35840
	ds_read_b128 v[210:213], v139 offset:36864
	ds_read_b128 v[214:217], v139 offset:37888
	ds_read_b128 v[218:221], v139 offset:38912
	ds_read_b128 v[222:225], v139 offset:39936
	global_load_lds_dwordx4 v[240:241], off
	v_lshl_add_u64 v[240:241], s[46:47], 0, v[132:133]
	s_mov_b32 m0, s42
	s_nop 0
	global_load_lds_dwordx4 v[240:241], off
	s_waitcnt vmcnt(8)
	s_waitcnt lgkmcnt(0)
	s_barrier
	s_setprio 1
	v_mfma_f32_16x16x32_bf16 v[112:115], v[140:143], v[172:175], v[112:115]
	v_mfma_f32_16x16x32_bf16 v[116:119], v[148:151], v[172:175], v[116:119]
	v_mfma_f32_16x16x32_bf16 v[96:99], v[140:143], v[202:205], v[96:99]
	v_mfma_f32_16x16x32_bf16 v[100:103], v[148:151], v[202:205], v[100:103]
	v_mfma_f32_16x16x32_bf16 v[72:75], v[140:143], v[210:213], v[72:75]
	v_mfma_f32_16x16x32_bf16 v[80:83], v[148:151], v[210:213], v[80:83]
	v_mfma_f32_16x16x32_bf16 v[40:43], v[140:143], v[218:221], v[40:43]
	v_mfma_f32_16x16x32_bf16 v[48:51], v[148:151], v[218:221], v[48:51]
	v_mfma_f32_16x16x32_bf16 v[112:115], v[144:147], v[198:201], v[112:115]
	v_mfma_f32_16x16x32_bf16 v[116:119], v[152:155], v[198:201], v[116:119]
	v_mfma_f32_16x16x32_bf16 v[96:99], v[144:147], v[206:209], v[96:99]
	v_mfma_f32_16x16x32_bf16 v[100:103], v[152:155], v[206:209], v[100:103]
	v_mfma_f32_16x16x32_bf16 v[72:75], v[144:147], v[214:217], v[72:75]
	v_mfma_f32_16x16x32_bf16 v[80:83], v[152:155], v[214:217], v[80:83]
	v_mfma_f32_16x16x32_bf16 v[40:43], v[144:147], v[222:225], v[40:43]
	v_mfma_f32_16x16x32_bf16 v[48:51], v[152:155], v[222:225], v[48:51]
	v_mfma_f32_16x16x32_bf16 v[120:123], v[156:159], v[172:175], v[120:123]
	v_mfma_f32_16x16x32_bf16 v[124:127], v[164:167], v[172:175], v[124:127]
	v_mfma_f32_16x16x32_bf16 v[104:107], v[156:159], v[202:205], v[104:107]
	v_mfma_f32_16x16x32_bf16 v[108:111], v[164:167], v[202:205], v[108:111]
	v_mfma_f32_16x16x32_bf16 v[88:91], v[156:159], v[210:213], v[88:91]
	v_mfma_f32_16x16x32_bf16 v[92:95], v[164:167], v[210:213], v[92:95]
	v_mfma_f32_16x16x32_bf16 v[64:67], v[156:159], v[218:221], v[64:67]
	v_mfma_f32_16x16x32_bf16 v[68:71], v[164:167], v[218:221], v[68:71]
	v_mfma_f32_16x16x32_bf16 v[120:123], v[160:163], v[198:201], v[120:123]
	v_mfma_f32_16x16x32_bf16 v[124:127], v[168:171], v[198:201], v[124:127]
	v_mfma_f32_16x16x32_bf16 v[104:107], v[160:163], v[206:209], v[104:107]
	v_mfma_f32_16x16x32_bf16 v[108:111], v[168:171], v[206:209], v[108:111]
	v_mfma_f32_16x16x32_bf16 v[88:91], v[160:163], v[214:217], v[88:91]
	v_mfma_f32_16x16x32_bf16 v[92:95], v[168:171], v[214:217], v[92:95]
	v_mfma_f32_16x16x32_bf16 v[64:67], v[160:163], v[222:225], v[64:67]
	v_mfma_f32_16x16x32_bf16 v[68:71], v[168:171], v[222:225], v[68:71]
	s_setprio 0
	s_barrier
	s_mov_b32 m0, s73
	v_lshl_add_u64 v[176:177], v[176:177], 0, s[90:91]
	ds_read_b128 v[172:175], v139 offset:49152
	ds_read_b128 v[198:201], v139 offset:50176
	ds_read_b128 v[202:205], v139 offset:51200
	ds_read_b128 v[206:209], v139 offset:52224
	ds_read_b128 v[210:213], v139 offset:53248
	ds_read_b128 v[214:217], v139 offset:54272
	ds_read_b128 v[218:221], v139 offset:55296
	ds_read_b128 v[222:225], v139 offset:56320
	global_load_lds_dwordx4 v[176:177], off
	v_lshl_add_u64 v[176:177], v[226:227], 0, s[90:91]
	s_mov_b32 m0, s59
	s_nop 0
	global_load_lds_dwordx4 v[176:177], off
	v_lshl_add_u64 v[176:177], s[44:45], 0, v[128:129]
	s_mov_b32 m0, s81
	s_nop 0
	global_load_lds_dwordx4 v[176:177], off
	v_lshl_add_u64 v[176:177], s[44:45], 0, v[130:131]
	s_mov_b32 m0, s74
	s_nop 0
	global_load_lds_dwordx4 v[176:177], off
	v_lshl_add_u64 v[176:177], v[228:229], 0, s[90:91]
	s_mov_b32 m0, s43
	s_nop 0
	global_load_lds_dwordx4 v[176:177], off
	v_lshl_add_u64 v[176:177], v[238:239], 0, s[90:91]
	s_mov_b32 m0, s52
	s_nop 0
	global_load_lds_dwordx4 v[176:177], off
	s_waitcnt vmcnt(8)
	s_waitcnt lgkmcnt(0)
	s_barrier
	s_setprio 1
	v_mfma_f32_16x16x32_bf16 v[56:59], v[140:143], v[172:175], v[56:59]
	v_mfma_f32_16x16x32_bf16 v[60:63], v[148:151], v[172:175], v[60:63]
	v_mfma_f32_16x16x32_bf16 v[32:35], v[140:143], v[202:205], v[32:35]
	v_mfma_f32_16x16x32_bf16 v[36:39], v[148:151], v[202:205], v[36:39]
	v_mfma_f32_16x16x32_bf16 v[16:19], v[140:143], v[210:213], v[16:19]
	v_mfma_f32_16x16x32_bf16 v[20:23], v[148:151], v[210:213], v[20:23]
	v_mfma_f32_16x16x32_bf16 v[0:3], v[140:143], v[218:221], v[0:3]
	v_mfma_f32_16x16x32_bf16 v[4:7], v[148:151], v[218:221], v[4:7]
	v_mfma_f32_16x16x32_bf16 v[56:59], v[144:147], v[198:201], v[56:59]
	v_mfma_f32_16x16x32_bf16 v[60:63], v[152:155], v[198:201], v[60:63]
	v_mfma_f32_16x16x32_bf16 v[32:35], v[144:147], v[206:209], v[32:35]
	v_mfma_f32_16x16x32_bf16 v[36:39], v[152:155], v[206:209], v[36:39]
	v_mfma_f32_16x16x32_bf16 v[16:19], v[144:147], v[214:217], v[16:19]
	v_mfma_f32_16x16x32_bf16 v[20:23], v[152:155], v[214:217], v[20:23]
	v_mfma_f32_16x16x32_bf16 v[0:3], v[144:147], v[222:225], v[0:3]
	v_mfma_f32_16x16x32_bf16 v[4:7], v[152:155], v[222:225], v[4:7]
	v_mfma_f32_16x16x32_bf16 v[76:79], v[156:159], v[172:175], v[76:79]
	v_mfma_f32_16x16x32_bf16 v[84:87], v[164:167], v[172:175], v[84:87]
	v_mfma_f32_16x16x32_bf16 v[44:47], v[156:159], v[202:205], v[44:47]
	v_mfma_f32_16x16x32_bf16 v[52:55], v[164:167], v[202:205], v[52:55]
	v_mfma_f32_16x16x32_bf16 v[24:27], v[156:159], v[210:213], v[24:27]
	v_mfma_f32_16x16x32_bf16 v[28:31], v[164:167], v[210:213], v[28:31]
	v_mfma_f32_16x16x32_bf16 v[8:11], v[156:159], v[218:221], v[8:11]
	v_mfma_f32_16x16x32_bf16 v[12:15], v[164:167], v[218:221], v[12:15]
	v_mfma_f32_16x16x32_bf16 v[76:79], v[160:163], v[198:201], v[76:79]
	v_mfma_f32_16x16x32_bf16 v[84:87], v[168:171], v[198:201], v[84:87]
	v_mfma_f32_16x16x32_bf16 v[44:47], v[160:163], v[206:209], v[44:47]
	v_mfma_f32_16x16x32_bf16 v[52:55], v[168:171], v[206:209], v[52:55]
	v_mfma_f32_16x16x32_bf16 v[24:27], v[160:163], v[214:217], v[24:27]
	v_mfma_f32_16x16x32_bf16 v[28:31], v[168:171], v[214:217], v[28:31]
	v_mfma_f32_16x16x32_bf16 v[8:11], v[160:163], v[222:225], v[8:11]
	v_mfma_f32_16x16x32_bf16 v[12:15], v[168:171], v[222:225], v[12:15]
	s_setprio 0
	s_barrier
	s_movk_i32 s46, 0x100
	s_andn2_b64 vcc, exec, s[38:39]
	s_mov_b64 s[44:45], -1
	s_mov_b64 s[38:39], 0
	s_cbranch_vccz .LBB0_344
	s_and_b64 vcc, exec, s[14:15]
	s_cbranch_vccz .LBB0_347
	s_barrier

.LBB0_360:
	s_add_u32 s39, s18, s38
	s_addc_u32 s48, s19, 0
	s_add_u32 s44, s39, 0x100
	s_addc_u32 s45, s48, 0
	s_and_b64 s[30:31], s[36:37], exec
	s_cselect_b32 s45, s15, s45
	s_cselect_b32 s44, s55, s44
	s_add_u32 s30, s24, s38
	s_addc_u32 s31, s25, 0
	s_add_u32 s38, s30, 0x100
	s_addc_u32 s46, s31, 0
	s_add_i32 s59, 0, 0x10000
	s_and_b64 s[30:31], s[36:37], exec
	s_cselect_b32 s47, s13, s46
	s_cselect_b32 s46, s56, s38
	s_add_i32 s37, 0, 0x14000
	s_add_u32 s30, s39, 0x10080
	s_addc_u32 s31, s48, 0
	s_add_i32 s67, s59, s40
	s_add_i32 m0, s17, 0xc000
	s_add_i32 s61, s17, 0xe000
	s_add_i32 s73, s67, 0x2000
	s_add_u32 s48, s46, 0x10000
	v_add_u32_e32 v152, s59, v137
	v_add_u32_e32 v168, s37, v137
	s_addc_u32 s49, s47, 0
	s_add_i32 s74, s37, s40
	ds_read_b128 v[140:143], v152
	ds_read_b128 v[144:147], v152 offset:1024
	ds_read_b128 v[148:151], v152 offset:2048
	ds_read_b128 v[152:155], v152 offset:3072
	ds_read_b128 v[156:159], v168
	ds_read_b128 v[160:163], v168 offset:1024
	ds_read_b128 v[164:167], v168 offset:2048
	ds_read_b128 v[168:171], v168 offset:3072
	s_add_i32 s81, s74, 0x2000
	s_add_i32 s82, 0, 0x18000
	s_add_i32 s83, 0, 0x1c000
	s_add_u32 s38, s44, 0x10000
	s_addc_u32 s39, s45, 0
	s_add_i32 s58, s82, s40
	s_add_i32 s57, s58, 0x2000
	s_add_u32 s36, s46, 0x10080
	s_addc_u32 s37, s47, 0
	s_add_i32 s60, s83, s40
	s_add_i32 s59, s60, 0x2000
	v_lshl_add_u64 v[176:177], s[30:31], 0, v[134:135]
	ds_read_b128 v[172:175], v139
	ds_read_b128 v[198:201], v139 offset:1024
	ds_read_b128 v[202:205], v139 offset:2048
	ds_read_b128 v[206:209], v139 offset:3072
	ds_read_b128 v[210:213], v139 offset:4096
	ds_read_b128 v[214:217], v139 offset:5120
	ds_read_b128 v[218:221], v139 offset:6144
	ds_read_b128 v[222:225], v139 offset:7168
	global_load_lds_dwordx4 v[176:177], off
	v_lshl_add_u64 v[176:177], s[30:31], 0, v[132:133]
	s_mov_b32 m0, s61
	s_nop 0
	global_load_lds_dwordx4 v[176:177], off
	s_waitcnt vmcnt(8)
	s_waitcnt lgkmcnt(0)
	s_barrier
	s_setprio 1
	v_mfma_f32_16x16x32_bf16 v[108:111], v[140:143], v[172:175], v[108:111]
	v_mfma_f32_16x16x32_bf16 v[116:119], v[148:151], v[172:175], v[116:119]
	v_mfma_f32_16x16x32_bf16 v[92:95], v[140:143], v[202:205], v[92:95]
	v_mfma_f32_16x16x32_bf16 v[100:103], v[148:151], v[202:205], v[100:103]
	v_mfma_f32_16x16x32_bf16 v[68:71], v[140:143], v[210:213], v[68:71]
	v_mfma_f32_16x16x32_bf16 v[76:79], v[148:151], v[210:213], v[76:79]
	v_mfma_f32_16x16x32_bf16 v[40:43], v[140:143], v[218:221], v[40:43]
	v_mfma_f32_16x16x32_bf16 v[44:47], v[148:151], v[218:221], v[44:47]
	v_mfma_f32_16x16x32_bf16 v[108:111], v[144:147], v[198:201], v[108:111]
	v_mfma_f32_16x16x32_bf16 v[116:119], v[152:155], v[198:201], v[116:119]
	v_mfma_f32_16x16x32_bf16 v[92:95], v[144:147], v[206:209], v[92:95]
	v_mfma_f32_16x16x32_bf16 v[100:103], v[152:155], v[206:209], v[100:103]
	v_mfma_f32_16x16x32_bf16 v[68:71], v[144:147], v[214:217], v[68:71]
	v_mfma_f32_16x16x32_bf16 v[76:79], v[152:155], v[214:217], v[76:79]
	v_mfma_f32_16x16x32_bf16 v[40:43], v[144:147], v[222:225], v[40:43]
	v_mfma_f32_16x16x32_bf16 v[44:47], v[152:155], v[222:225], v[44:47]
	v_mfma_f32_16x16x32_bf16 v[120:123], v[156:159], v[172:175], v[120:123]
	v_mfma_f32_16x16x32_bf16 v[124:127], v[164:167], v[172:175], v[124:127]
	v_mfma_f32_16x16x32_bf16 v[104:107], v[156:159], v[202:205], v[104:107]
	v_mfma_f32_16x16x32_bf16 v[112:115], v[164:167], v[202:205], v[112:115]
	v_mfma_f32_16x16x32_bf16 v[88:91], v[156:159], v[210:213], v[88:91]
	v_mfma_f32_16x16x32_bf16 v[96:99], v[164:167], v[210:213], v[96:99]
	v_mfma_f32_16x16x32_bf16 v[64:67], v[156:159], v[218:221], v[64:67]
	v_mfma_f32_16x16x32_bf16 v[72:75], v[164:167], v[218:221], v[72:75]
	v_mfma_f32_16x16x32_bf16 v[120:123], v[160:163], v[198:201], v[120:123]
	v_mfma_f32_16x16x32_bf16 v[124:127], v[168:171], v[198:201], v[124:127]
	v_mfma_f32_16x16x32_bf16 v[104:107], v[160:163], v[206:209], v[104:107]
	v_mfma_f32_16x16x32_bf16 v[112:115], v[168:171], v[206:209], v[112:115]
	v_mfma_f32_16x16x32_bf16 v[88:91], v[160:163], v[214:217], v[88:91]
	v_mfma_f32_16x16x32_bf16 v[96:99], v[168:171], v[214:217], v[96:99]
	v_mfma_f32_16x16x32_bf16 v[64:67], v[160:163], v[222:225], v[64:67]
	v_mfma_f32_16x16x32_bf16 v[72:75], v[168:171], v[222:225], v[72:75]
	s_setprio 0
	s_barrier
	s_mov_b32 m0, s67
	v_lshl_add_u64 v[176:177], s[46:47], 0, v[128:129]
	ds_read_b128 v[172:175], v139 offset:16384
	ds_read_b128 v[198:201], v139 offset:17408
	ds_read_b128 v[202:205], v139 offset:18432
	ds_read_b128 v[206:209], v139 offset:19456
	ds_read_b128 v[210:213], v139 offset:20480
	ds_read_b128 v[214:217], v139 offset:21504
	ds_read_b128 v[218:221], v139 offset:22528
	ds_read_b128 v[222:225], v139 offset:23552
	global_load_lds_dwordx4 v[176:177], off
	v_lshl_add_u64 v[226:227], s[46:47], 0, v[130:131]
	s_mov_b32 m0, s73
	v_lshl_add_u64 v[228:229], s[48:49], 0, v[128:129]
	global_load_lds_dwordx4 v[226:227], off
	s_mov_b32 m0, s74
	v_lshl_add_u64 v[238:239], s[44:45], 0, v[132:133]
	global_load_lds_dwordx4 v[228:229], off
	v_lshl_add_u64 v[228:229], s[48:49], 0, v[130:131]
	s_mov_b32 m0, s81
	s_nop 0
	global_load_lds_dwordx4 v[228:229], off
	v_lshl_add_u64 v[228:229], s[44:45], 0, v[134:135]
	s_mov_b32 m0, s17
	s_nop 0
	global_load_lds_dwordx4 v[228:229], off
	s_mov_b32 m0, s20
	s_nop 0
	global_load_lds_dwordx4 v[238:239], off
	s_waitcnt vmcnt(8)
	s_waitcnt lgkmcnt(0)
	s_barrier
	s_setprio 1
	v_mfma_f32_16x16x32_bf16 v[52:55], v[140:143], v[172:175], v[52:55]
	v_mfma_f32_16x16x32_bf16 v[60:63], v[148:151], v[172:175], v[60:63]
	v_mfma_f32_16x16x32_bf16 v[28:31], v[140:143], v[202:205], v[28:31]
	v_mfma_f32_16x16x32_bf16 v[36:39], v[148:151], v[202:205], v[36:39]
	v_mfma_f32_16x16x32_bf16 v[12:15], v[140:143], v[210:213], v[12:15]
	v_mfma_f32_16x16x32_bf16 v[16:19], v[148:151], v[210:213], v[16:19]
	v_mfma_f32_16x16x32_bf16 v[0:3], v[140:143], v[218:221], v[0:3]
	v_mfma_f32_16x16x32_bf16 v[4:7], v[148:151], v[218:221], v[4:7]
	v_mfma_f32_16x16x32_bf16 v[52:55], v[144:147], v[198:201], v[52:55]
	v_mfma_f32_16x16x32_bf16 v[60:63], v[152:155], v[198:201], v[60:63]
	v_mfma_f32_16x16x32_bf16 v[28:31], v[144:147], v[206:209], v[28:31]
	v_mfma_f32_16x16x32_bf16 v[36:39], v[152:155], v[206:209], v[36:39]
	v_mfma_f32_16x16x32_bf16 v[12:15], v[144:147], v[214:217], v[12:15]
	v_mfma_f32_16x16x32_bf16 v[16:19], v[152:155], v[214:217], v[16:19]
	v_mfma_f32_16x16x32_bf16 v[0:3], v[144:147], v[222:225], v[0:3]
	v_mfma_f32_16x16x32_bf16 v[4:7], v[152:155], v[222:225], v[4:7]
	v_mfma_f32_16x16x32_bf16 v[80:83], v[156:159], v[172:175], v[80:83]
	v_mfma_f32_16x16x32_bf16 v[84:87], v[164:167], v[172:175], v[84:87]
	v_mfma_f32_16x16x32_bf16 v[48:51], v[156:159], v[202:205], v[48:51]
	v_mfma_f32_16x16x32_bf16 v[56:59], v[164:167], v[202:205], v[56:59]
	v_mfma_f32_16x16x32_bf16 v[24:27], v[156:159], v[210:213], v[24:27]
	v_mfma_f32_16x16x32_bf16 v[32:35], v[164:167], v[210:213], v[32:35]
	v_mfma_f32_16x16x32_bf16 v[8:11], v[156:159], v[218:221], v[8:11]
	v_mfma_f32_16x16x32_bf16 v[20:23], v[164:167], v[218:221], v[20:23]
	v_mfma_f32_16x16x32_bf16 v[80:83], v[160:163], v[198:201], v[80:83]
	v_mfma_f32_16x16x32_bf16 v[84:87], v[168:171], v[198:201], v[84:87]
	v_mfma_f32_16x16x32_bf16 v[48:51], v[160:163], v[206:209], v[48:51]
	v_mfma_f32_16x16x32_bf16 v[56:59], v[168:171], v[206:209], v[56:59]
	v_mfma_f32_16x16x32_bf16 v[24:27], v[160:163], v[214:217], v[24:27]
	v_mfma_f32_16x16x32_bf16 v[32:35], v[168:171], v[214:217], v[32:35]
	v_mfma_f32_16x16x32_bf16 v[8:11], v[160:163], v[222:225], v[8:11]
	v_mfma_f32_16x16x32_bf16 v[20:23], v[168:171], v[222:225], v[20:23]
	s_setprio 0
	s_barrier
	v_add_u32_e32 v152, s82, v137
	v_add_u32_e32 v168, s83, v137
	ds_read_b128 v[140:143], v152
	ds_read_b128 v[144:147], v152 offset:1024
	ds_read_b128 v[148:151], v152 offset:2048
	ds_read_b128 v[152:155], v152 offset:3072
	ds_read_b128 v[156:159], v168
	ds_read_b128 v[160:163], v168 offset:1024
	ds_read_b128 v[164:167], v168 offset:2048
	ds_read_b128 v[168:171], v168 offset:3072
	s_mov_b32 m0, s21
	v_lshl_add_u64 v[240:241], s[38:39], 0, v[134:135]
	ds_read_b128 v[172:175], v139 offset:32768
	ds_read_b128 v[198:201], v139 offset:33792
	ds_read_b128 v[202:205], v139 offset:34816
	ds_read_b128 v[206:209], v139 offset:35840
	ds_read_b128 v[210:213], v139 offset:36864
	ds_read_b128 v[214:217], v139 offset:37888
	ds_read_b128 v[218:221], v139 offset:38912
	ds_read_b128 v[222:225], v139 offset:39936
	global_load_lds_dwordx4 v[240:241], off
	v_lshl_add_u64 v[240:241], s[38:39], 0, v[132:133]
	s_mov_b32 m0, s42
	s_nop 0
	global_load_lds_dwordx4 v[240:241], off
	s_waitcnt vmcnt(8)
	s_waitcnt lgkmcnt(0)
	s_barrier
	s_setprio 1
	v_mfma_f32_16x16x32_bf16 v[108:111], v[140:143], v[172:175], v[108:111]
	v_mfma_f32_16x16x32_bf16 v[116:119], v[148:151], v[172:175], v[116:119]
	v_mfma_f32_16x16x32_bf16 v[92:95], v[140:143], v[202:205], v[92:95]
	v_mfma_f32_16x16x32_bf16 v[100:103], v[148:151], v[202:205], v[100:103]
	v_mfma_f32_16x16x32_bf16 v[68:71], v[140:143], v[210:213], v[68:71]
	v_mfma_f32_16x16x32_bf16 v[76:79], v[148:151], v[210:213], v[76:79]
	v_mfma_f32_16x16x32_bf16 v[40:43], v[140:143], v[218:221], v[40:43]
	v_mfma_f32_16x16x32_bf16 v[44:47], v[148:151], v[218:221], v[44:47]
	v_mfma_f32_16x16x32_bf16 v[108:111], v[144:147], v[198:201], v[108:111]
	v_mfma_f32_16x16x32_bf16 v[116:119], v[152:155], v[198:201], v[116:119]
	v_mfma_f32_16x16x32_bf16 v[92:95], v[144:147], v[206:209], v[92:95]
	v_mfma_f32_16x16x32_bf16 v[100:103], v[152:155], v[206:209], v[100:103]
	v_mfma_f32_16x16x32_bf16 v[68:71], v[144:147], v[214:217], v[68:71]
	v_mfma_f32_16x16x32_bf16 v[76:79], v[152:155], v[214:217], v[76:79]
	v_mfma_f32_16x16x32_bf16 v[40:43], v[144:147], v[222:225], v[40:43]
	v_mfma_f32_16x16x32_bf16 v[44:47], v[152:155], v[222:225], v[44:47]
	v_mfma_f32_16x16x32_bf16 v[120:123], v[156:159], v[172:175], v[120:123]
	v_mfma_f32_16x16x32_bf16 v[124:127], v[164:167], v[172:175], v[124:127]
	v_mfma_f32_16x16x32_bf16 v[104:107], v[156:159], v[202:205], v[104:107]
	v_mfma_f32_16x16x32_bf16 v[112:115], v[164:167], v[202:205], v[112:115]
	v_mfma_f32_16x16x32_bf16 v[88:91], v[156:159], v[210:213], v[88:91]
	v_mfma_f32_16x16x32_bf16 v[96:99], v[164:167], v[210:213], v[96:99]
	v_mfma_f32_16x16x32_bf16 v[64:67], v[156:159], v[218:221], v[64:67]
	v_mfma_f32_16x16x32_bf16 v[72:75], v[164:167], v[218:221], v[72:75]
	v_mfma_f32_16x16x32_bf16 v[120:123], v[160:163], v[198:201], v[120:123]
	v_mfma_f32_16x16x32_bf16 v[124:127], v[168:171], v[198:201], v[124:127]
	v_mfma_f32_16x16x32_bf16 v[104:107], v[160:163], v[206:209], v[104:107]
	v_mfma_f32_16x16x32_bf16 v[112:115], v[168:171], v[206:209], v[112:115]
	v_mfma_f32_16x16x32_bf16 v[88:91], v[160:163], v[214:217], v[88:91]
	v_mfma_f32_16x16x32_bf16 v[96:99], v[168:171], v[214:217], v[96:99]
	v_mfma_f32_16x16x32_bf16 v[64:67], v[160:163], v[222:225], v[64:67]
	v_mfma_f32_16x16x32_bf16 v[72:75], v[168:171], v[222:225], v[72:75]
	s_setprio 0
	s_barrier
	s_mov_b32 m0, s58
	v_lshl_add_u64 v[176:177], v[176:177], 0, s[90:91]
	ds_read_b128 v[172:175], v139 offset:49152
	ds_read_b128 v[198:201], v139 offset:50176
	ds_read_b128 v[202:205], v139 offset:51200
	ds_read_b128 v[206:209], v139 offset:52224
	ds_read_b128 v[210:213], v139 offset:53248
	ds_read_b128 v[214:217], v139 offset:54272
	ds_read_b128 v[218:221], v139 offset:55296
	ds_read_b128 v[222:225], v139 offset:56320
	global_load_lds_dwordx4 v[176:177], off
	v_lshl_add_u64 v[176:177], v[226:227], 0, s[90:91]
	s_mov_b32 m0, s57
	s_nop 0
	global_load_lds_dwordx4 v[176:177], off
	v_lshl_add_u64 v[176:177], s[36:37], 0, v[128:129]
	s_mov_b32 m0, s60
	s_nop 0
	global_load_lds_dwordx4 v[176:177], off
	v_lshl_add_u64 v[176:177], s[36:37], 0, v[130:131]
	s_mov_b32 m0, s59
	s_nop 0
	global_load_lds_dwordx4 v[176:177], off
	v_lshl_add_u64 v[176:177], v[228:229], 0, s[90:91]
	s_mov_b32 m0, s43
	s_nop 0
	global_load_lds_dwordx4 v[176:177], off
	v_lshl_add_u64 v[176:177], v[238:239], 0, s[90:91]
	s_mov_b32 m0, s50
	s_nop 0
	global_load_lds_dwordx4 v[176:177], off
	s_waitcnt vmcnt(8)
	s_waitcnt lgkmcnt(0)
	s_barrier
	s_setprio 1
	v_mfma_f32_16x16x32_bf16 v[52:55], v[140:143], v[172:175], v[52:55]
	v_mfma_f32_16x16x32_bf16 v[60:63], v[148:151], v[172:175], v[60:63]
	v_mfma_f32_16x16x32_bf16 v[28:31], v[140:143], v[202:205], v[28:31]
	v_mfma_f32_16x16x32_bf16 v[36:39], v[148:151], v[202:205], v[36:39]
	v_mfma_f32_16x16x32_bf16 v[12:15], v[140:143], v[210:213], v[12:15]
	v_mfma_f32_16x16x32_bf16 v[16:19], v[148:151], v[210:213], v[16:19]
	v_mfma_f32_16x16x32_bf16 v[0:3], v[140:143], v[218:221], v[0:3]
	v_mfma_f32_16x16x32_bf16 v[4:7], v[148:151], v[218:221], v[4:7]
	v_mfma_f32_16x16x32_bf16 v[52:55], v[144:147], v[198:201], v[52:55]
	v_mfma_f32_16x16x32_bf16 v[60:63], v[152:155], v[198:201], v[60:63]
	v_mfma_f32_16x16x32_bf16 v[28:31], v[144:147], v[206:209], v[28:31]
	v_mfma_f32_16x16x32_bf16 v[36:39], v[152:155], v[206:209], v[36:39]
	v_mfma_f32_16x16x32_bf16 v[12:15], v[144:147], v[214:217], v[12:15]
	v_mfma_f32_16x16x32_bf16 v[16:19], v[152:155], v[214:217], v[16:19]
	v_mfma_f32_16x16x32_bf16 v[0:3], v[144:147], v[222:225], v[0:3]
	v_mfma_f32_16x16x32_bf16 v[4:7], v[152:155], v[222:225], v[4:7]
	v_mfma_f32_16x16x32_bf16 v[80:83], v[156:159], v[172:175], v[80:83]
	v_mfma_f32_16x16x32_bf16 v[84:87], v[164:167], v[172:175], v[84:87]
	v_mfma_f32_16x16x32_bf16 v[48:51], v[156:159], v[202:205], v[48:51]
	v_mfma_f32_16x16x32_bf16 v[56:59], v[164:167], v[202:205], v[56:59]
	v_mfma_f32_16x16x32_bf16 v[24:27], v[156:159], v[210:213], v[24:27]
	v_mfma_f32_16x16x32_bf16 v[32:35], v[164:167], v[210:213], v[32:35]
	v_mfma_f32_16x16x32_bf16 v[8:11], v[156:159], v[218:221], v[8:11]
	v_mfma_f32_16x16x32_bf16 v[20:23], v[164:167], v[218:221], v[20:23]
	v_mfma_f32_16x16x32_bf16 v[80:83], v[160:163], v[198:201], v[80:83]
	v_mfma_f32_16x16x32_bf16 v[84:87], v[168:171], v[198:201], v[84:87]
	v_mfma_f32_16x16x32_bf16 v[48:51], v[160:163], v[206:209], v[48:51]
	v_mfma_f32_16x16x32_bf16 v[56:59], v[168:171], v[206:209], v[56:59]
	v_mfma_f32_16x16x32_bf16 v[24:27], v[160:163], v[214:217], v[24:27]
	v_mfma_f32_16x16x32_bf16 v[32:35], v[168:171], v[214:217], v[32:35]
	v_mfma_f32_16x16x32_bf16 v[8:11], v[160:163], v[222:225], v[8:11]
	v_mfma_f32_16x16x32_bf16 v[20:23], v[168:171], v[222:225], v[20:23]
	s_setprio 0
	s_barrier
	s_movk_i32 s38, 0x100
	s_andn2_b64 vcc, exec, s[34:35]
	s_mov_b64 s[36:37], -1
	s_mov_b64 s[34:35], 0
	s_cbranch_vccz .LBB0_360
	s_and_b64 vcc, exec, s[10:11]
	s_cbranch_vccz .LBB0_363
	s_barrier

.LBB0_395:
	s_add_u32 s16, s14, 0xfffc0080
	s_addc_u32 s17, s15, -1
	s_add_i32 s30, 0, 0x10000
	s_cmp_eq_u32 s48, 12
	s_cselect_b32 s27, s21, s17
	s_cselect_b32 s26, s44, s16
	v_add_u32_e32 v142, s30, v145
	s_cselect_b32 s17, s19, s47
	s_cselect_b32 s16, s45, s46
	s_add_i32 s49, 0, 0x14000
	ds_read_b128 v[146:149], v142
	ds_read_b128 v[150:153], v142 offset:1024
	ds_read_b128 v[154:157], v142 offset:2048
	ds_read_b128 v[158:161], v142 offset:3072
	v_add_u32_e32 v142, s49, v145
	ds_read_b128 v[162:165], v142
	ds_read_b128 v[166:169], v142 offset:1024
	ds_read_b128 v[170:173], v142 offset:2048
	ds_read_b128 v[174:177], v142 offset:3072
	v_lshl_add_u64 v[142:143], s[14:15], 0, v[138:139]
	s_add_i32 m0, s9, 0xc000
	ds_read_b128 v[198:201], v141
	ds_read_b128 v[202:205], v141 offset:1024
	ds_read_b128 v[206:209], v141 offset:2048
	ds_read_b128 v[210:213], v141 offset:3072
	ds_read_b128 v[214:217], v141 offset:4096
	ds_read_b128 v[218:221], v141 offset:5120
	ds_read_b128 v[222:225], v141 offset:6144
	ds_read_b128 v[226:229], v141 offset:7168
	global_load_lds_dwordx4 v[142:143], off
	v_lshl_add_u64 v[142:143], s[14:15], 0, v[136:137]
	s_add_i32 m0, s9, 0xe000
	s_nop 0
	global_load_lds_dwordx4 v[142:143], off
	s_waitcnt vmcnt(8)
	s_waitcnt lgkmcnt(0)
	s_barrier
	s_setprio 1
	v_mfma_f32_16x16x32_bf16 v[20:23], v[146:149], v[198:201], v[20:23]
	v_mfma_f32_16x16x32_bf16 v[28:31], v[154:157], v[198:201], v[28:31]
	v_mfma_f32_16x16x32_bf16 v[12:15], v[146:149], v[206:209], v[12:15]
	v_mfma_f32_16x16x32_bf16 v[24:27], v[154:157], v[206:209], v[24:27]
	v_mfma_f32_16x16x32_bf16 v[4:7], v[146:149], v[214:217], v[4:7]
	v_mfma_f32_16x16x32_bf16 v[16:19], v[154:157], v[214:217], v[16:19]
	v_mfma_f32_16x16x32_bf16 v[0:3], v[146:149], v[222:225], v[0:3]
	v_mfma_f32_16x16x32_bf16 v[8:11], v[154:157], v[222:225], v[8:11]
	v_mfma_f32_16x16x32_bf16 v[20:23], v[150:153], v[202:205], v[20:23]
	v_mfma_f32_16x16x32_bf16 v[28:31], v[158:161], v[202:205], v[28:31]
	v_mfma_f32_16x16x32_bf16 v[12:15], v[150:153], v[210:213], v[12:15]
	v_mfma_f32_16x16x32_bf16 v[24:27], v[158:161], v[210:213], v[24:27]
	v_mfma_f32_16x16x32_bf16 v[4:7], v[150:153], v[218:221], v[4:7]
	v_mfma_f32_16x16x32_bf16 v[16:19], v[158:161], v[218:221], v[16:19]
	v_mfma_f32_16x16x32_bf16 v[0:3], v[150:153], v[226:229], v[0:3]
	v_mfma_f32_16x16x32_bf16 v[8:11], v[158:161], v[226:229], v[8:11]
	v_mfma_f32_16x16x32_bf16 v[84:87], v[162:165], v[198:201], v[84:87]
	v_mfma_f32_16x16x32_bf16 v[92:95], v[170:173], v[198:201], v[92:95]
	v_mfma_f32_16x16x32_bf16 v[72:75], v[162:165], v[206:209], v[72:75]
	v_mfma_f32_16x16x32_bf16 v[88:91], v[170:173], v[206:209], v[88:91]
	v_mfma_f32_16x16x32_bf16 v[60:63], v[162:165], v[214:217], v[60:63]
	v_mfma_f32_16x16x32_bf16 v[80:83], v[170:173], v[214:217], v[80:83]
	v_mfma_f32_16x16x32_bf16 v[48:51], v[162:165], v[222:225], v[48:51]
	v_mfma_f32_16x16x32_bf16 v[68:71], v[170:173], v[222:225], v[68:71]
	v_mfma_f32_16x16x32_bf16 v[84:87], v[166:169], v[202:205], v[84:87]
	v_mfma_f32_16x16x32_bf16 v[92:95], v[174:177], v[202:205], v[92:95]
	v_mfma_f32_16x16x32_bf16 v[72:75], v[166:169], v[210:213], v[72:75]
	v_mfma_f32_16x16x32_bf16 v[88:91], v[174:177], v[210:213], v[88:91]
	v_mfma_f32_16x16x32_bf16 v[60:63], v[166:169], v[218:221], v[60:63]
	v_mfma_f32_16x16x32_bf16 v[80:83], v[174:177], v[218:221], v[80:83]
	v_mfma_f32_16x16x32_bf16 v[48:51], v[166:169], v[226:229], v[48:51]
	v_mfma_f32_16x16x32_bf16 v[68:71], v[174:177], v[226:229], v[68:71]
	s_setprio 0
	s_barrier
	s_add_i32 s30, s30, s34
	v_lshl_add_u64 v[142:143], s[16:17], 0, v[128:129]
	s_mov_b32 m0, s30
	ds_read_b128 v[198:201], v141 offset:16384
	ds_read_b128 v[202:205], v141 offset:17408
	ds_read_b128 v[206:209], v141 offset:18432
	ds_read_b128 v[210:213], v141 offset:19456
	ds_read_b128 v[214:217], v141 offset:20480
	ds_read_b128 v[218:221], v141 offset:21504
	ds_read_b128 v[222:225], v141 offset:22528
	ds_read_b128 v[226:229], v141 offset:23552
	global_load_lds_dwordx4 v[142:143], off
	s_add_i32 m0, s30, 0x2000
	s_add_u32 s30, s16, 0x40000
	v_lshl_add_u64 v[238:239], s[16:17], 0, v[130:131]
	s_addc_u32 s31, s17, 0
	s_add_i32 s49, s49, s34
	global_load_lds_dwordx4 v[238:239], off
	v_lshl_add_u64 v[240:241], s[30:31], 0, v[128:129]
	s_mov_b32 m0, s49
	v_lshl_add_u64 v[242:243], s[26:27], 0, v[132:133]
	global_load_lds_dwordx4 v[240:241], off
	v_lshl_add_u64 v[240:241], s[30:31], 0, v[130:131]
	s_add_i32 m0, s49, 0x2000
	s_nop 0
	global_load_lds_dwordx4 v[240:241], off
	v_lshl_add_u64 v[240:241], s[26:27], 0, v[134:135]
	s_mov_b32 m0, s9
	s_nop 0
	global_load_lds_dwordx4 v[240:241], off
	s_mov_b32 m0, s36
	s_nop 0
	global_load_lds_dwordx4 v[242:243], off
	s_waitcnt vmcnt(8)
	s_waitcnt lgkmcnt(0)
	s_barrier
	s_setprio 1
	v_mfma_f32_16x16x32_bf16 v[56:59], v[146:149], v[198:201], v[56:59]
	v_mfma_f32_16x16x32_bf16 v[76:79], v[154:157], v[198:201], v[76:79]
	v_mfma_f32_16x16x32_bf16 v[44:47], v[146:149], v[206:209], v[44:47]
	v_mfma_f32_16x16x32_bf16 v[64:67], v[154:157], v[206:209], v[64:67]
	v_mfma_f32_16x16x32_bf16 v[36:39], v[146:149], v[214:217], v[36:39]
	v_mfma_f32_16x16x32_bf16 v[52:55], v[154:157], v[214:217], v[52:55]
	v_mfma_f32_16x16x32_bf16 v[32:35], v[146:149], v[222:225], v[32:35]
	v_mfma_f32_16x16x32_bf16 v[40:43], v[154:157], v[222:225], v[40:43]
	v_mfma_f32_16x16x32_bf16 v[56:59], v[150:153], v[202:205], v[56:59]
	v_mfma_f32_16x16x32_bf16 v[76:79], v[158:161], v[202:205], v[76:79]
	v_mfma_f32_16x16x32_bf16 v[44:47], v[150:153], v[210:213], v[44:47]
	v_mfma_f32_16x16x32_bf16 v[64:67], v[158:161], v[210:213], v[64:67]
	v_mfma_f32_16x16x32_bf16 v[36:39], v[150:153], v[218:221], v[36:39]
	v_mfma_f32_16x16x32_bf16 v[52:55], v[158:161], v[218:221], v[52:55]
	v_mfma_f32_16x16x32_bf16 v[32:35], v[150:153], v[226:229], v[32:35]
	v_mfma_f32_16x16x32_bf16 v[40:43], v[158:161], v[226:229], v[40:43]
	v_mfma_f32_16x16x32_bf16 v[112:115], v[162:165], v[198:201], v[112:115]
	v_mfma_f32_16x16x32_bf16 v[120:123], v[170:173], v[198:201], v[120:123]
	v_mfma_f32_16x16x32_bf16 v[104:107], v[162:165], v[206:209], v[104:107]
	v_mfma_f32_16x16x32_bf16 v[116:119], v[170:173], v[206:209], v[116:119]
	v_mfma_f32_16x16x32_bf16 v[100:103], v[162:165], v[214:217], v[100:103]
	v_mfma_f32_16x16x32_bf16 v[108:111], v[170:173], v[214:217], v[108:111]
	v_mfma_f32_16x16x32_bf16 v[96:99], v[162:165], v[222:225], v[96:99]
	v_mfma_f32_16x16x32_bf16 v[124:127], v[170:173], v[222:225], v[124:127]
	v_mfma_f32_16x16x32_bf16 v[112:115], v[166:169], v[202:205], v[112:115]
	v_mfma_f32_16x16x32_bf16 v[120:123], v[174:177], v[202:205], v[120:123]
	v_mfma_f32_16x16x32_bf16 v[104:107], v[166:169], v[210:213], v[104:107]
	v_mfma_f32_16x16x32_bf16 v[116:119], v[174:177], v[210:213], v[116:119]
	v_mfma_f32_16x16x32_bf16 v[100:103], v[166:169], v[218:221], v[100:103]
	v_mfma_f32_16x16x32_bf16 v[108:111], v[174:177], v[218:221], v[108:111]
	v_mfma_f32_16x16x32_bf16 v[96:99], v[166:169], v[226:229], v[96:99]
	v_mfma_f32_16x16x32_bf16 v[124:127], v[174:177], v[226:229], v[124:127]
	s_setprio 0
	s_barrier
	s_add_i32 s30, 0, 0x18000
	s_add_i32 s31, 0, 0x1c000
	v_add_u32_e32 v158, s30, v145
	v_add_u32_e32 v174, s31, v145
	ds_read_b128 v[146:149], v158
	ds_read_b128 v[150:153], v158 offset:1024
	ds_read_b128 v[154:157], v158 offset:2048
	ds_read_b128 v[158:161], v158 offset:3072
	ds_read_b128 v[162:165], v174
	ds_read_b128 v[166:169], v174 offset:1024
	ds_read_b128 v[170:173], v174 offset:2048
	ds_read_b128 v[174:177], v174 offset:3072
	s_add_u32 s26, s26, 0x40000
	s_addc_u32 s27, s27, 0
	s_mov_b32 m0, s37
	v_lshl_add_u64 v[244:245], s[26:27], 0, v[134:135]
	ds_read_b128 v[198:201], v141 offset:32768
	ds_read_b128 v[202:205], v141 offset:33792
	ds_read_b128 v[206:209], v141 offset:34816
	ds_read_b128 v[210:213], v141 offset:35840
	ds_read_b128 v[214:217], v141 offset:36864
	ds_read_b128 v[218:221], v141 offset:37888
	ds_read_b128 v[222:225], v141 offset:38912
	ds_read_b128 v[226:229], v141 offset:39936
	global_load_lds_dwordx4 v[244:245], off
	v_lshl_add_u64 v[244:245], s[26:27], 0, v[132:133]
	s_mov_b32 m0, s38
	s_nop 0
	global_load_lds_dwordx4 v[244:245], off
	s_waitcnt vmcnt(8)
	s_waitcnt lgkmcnt(0)
	s_barrier
	s_setprio 1
	v_mfma_f32_16x16x32_bf16 v[20:23], v[146:149], v[198:201], v[20:23]
	v_mfma_f32_16x16x32_bf16 v[28:31], v[154:157], v[198:201], v[28:31]
	v_mfma_f32_16x16x32_bf16 v[12:15], v[146:149], v[206:209], v[12:15]
	v_mfma_f32_16x16x32_bf16 v[24:27], v[154:157], v[206:209], v[24:27]
	v_mfma_f32_16x16x32_bf16 v[4:7], v[146:149], v[214:217], v[4:7]
	v_mfma_f32_16x16x32_bf16 v[16:19], v[154:157], v[214:217], v[16:19]
	v_mfma_f32_16x16x32_bf16 v[0:3], v[146:149], v[222:225], v[0:3]
	v_mfma_f32_16x16x32_bf16 v[8:11], v[154:157], v[222:225], v[8:11]
	v_mfma_f32_16x16x32_bf16 v[20:23], v[150:153], v[202:205], v[20:23]
	v_mfma_f32_16x16x32_bf16 v[28:31], v[158:161], v[202:205], v[28:31]
	v_mfma_f32_16x16x32_bf16 v[12:15], v[150:153], v[210:213], v[12:15]
	v_mfma_f32_16x16x32_bf16 v[24:27], v[158:161], v[210:213], v[24:27]
	v_mfma_f32_16x16x32_bf16 v[4:7], v[150:153], v[218:221], v[4:7]
	v_mfma_f32_16x16x32_bf16 v[16:19], v[158:161], v[218:221], v[16:19]
	v_mfma_f32_16x16x32_bf16 v[0:3], v[150:153], v[226:229], v[0:3]
	v_mfma_f32_16x16x32_bf16 v[8:11], v[158:161], v[226:229], v[8:11]
	v_mfma_f32_16x16x32_bf16 v[84:87], v[162:165], v[198:201], v[84:87]
	v_mfma_f32_16x16x32_bf16 v[92:95], v[170:173], v[198:201], v[92:95]
	v_mfma_f32_16x16x32_bf16 v[72:75], v[162:165], v[206:209], v[72:75]
	v_mfma_f32_16x16x32_bf16 v[88:91], v[170:173], v[206:209], v[88:91]
	v_mfma_f32_16x16x32_bf16 v[60:63], v[162:165], v[214:217], v[60:63]
	v_mfma_f32_16x16x32_bf16 v[80:83], v[170:173], v[214:217], v[80:83]
	v_mfma_f32_16x16x32_bf16 v[48:51], v[162:165], v[222:225], v[48:51]
	v_mfma_f32_16x16x32_bf16 v[68:71], v[170:173], v[222:225], v[68:71]
	v_mfma_f32_16x16x32_bf16 v[84:87], v[166:169], v[202:205], v[84:87]
	v_mfma_f32_16x16x32_bf16 v[92:95], v[174:177], v[202:205], v[92:95]
	v_mfma_f32_16x16x32_bf16 v[72:75], v[166:169], v[210:213], v[72:75]
	v_mfma_f32_16x16x32_bf16 v[88:91], v[174:177], v[210:213], v[88:91]
	v_mfma_f32_16x16x32_bf16 v[60:63], v[166:169], v[218:221], v[60:63]
	v_mfma_f32_16x16x32_bf16 v[80:83], v[174:177], v[218:221], v[80:83]
	v_mfma_f32_16x16x32_bf16 v[48:51], v[166:169], v[226:229], v[48:51]
	v_mfma_f32_16x16x32_bf16 v[68:71], v[174:177], v[226:229], v[68:71]
	s_setprio 0
	s_barrier
	s_add_i32 s26, s30, s34
	v_lshl_add_u64 v[142:143], v[142:143], 0, s[90:91]
	s_mov_b32 m0, s26
	ds_read_b128 v[198:201], v141 offset:49152
	ds_read_b128 v[202:205], v141 offset:50176
	ds_read_b128 v[206:209], v141 offset:51200
	ds_read_b128 v[210:213], v141 offset:52224
	ds_read_b128 v[214:217], v141 offset:53248
	ds_read_b128 v[218:221], v141 offset:54272
	ds_read_b128 v[222:225], v141 offset:55296
	ds_read_b128 v[226:229], v141 offset:56320
	global_load_lds_dwordx4 v[142:143], off
	s_add_i32 m0, s26, 0x2000
	s_add_u32 s16, s16, 0x40080
	v_lshl_add_u64 v[142:143], v[238:239], 0, s[90:91]
	s_addc_u32 s17, s17, 0
	s_add_i32 s26, s31, s34
	global_load_lds_dwordx4 v[142:143], off
	v_lshl_add_u64 v[142:143], s[16:17], 0, v[128:129]
	s_mov_b32 m0, s26
	s_nop 0
	global_load_lds_dwordx4 v[142:143], off
	v_lshl_add_u64 v[142:143], s[16:17], 0, v[130:131]
	s_add_i32 m0, s26, 0x2000
	s_nop 0
	global_load_lds_dwordx4 v[142:143], off
	v_lshl_add_u64 v[142:143], v[240:241], 0, s[90:91]
	s_mov_b32 m0, s40
	s_nop 0
	global_load_lds_dwordx4 v[142:143], off
	v_lshl_add_u64 v[142:143], v[242:243], 0, s[90:91]
	s_mov_b32 m0, s41
	s_nop 0
	global_load_lds_dwordx4 v[142:143], off
	s_waitcnt vmcnt(8)
	s_waitcnt lgkmcnt(0)
	s_barrier
	s_setprio 1
	v_mfma_f32_16x16x32_bf16 v[56:59], v[146:149], v[198:201], v[56:59]
	v_mfma_f32_16x16x32_bf16 v[76:79], v[154:157], v[198:201], v[76:79]
	v_mfma_f32_16x16x32_bf16 v[44:47], v[146:149], v[206:209], v[44:47]
	v_mfma_f32_16x16x32_bf16 v[64:67], v[154:157], v[206:209], v[64:67]
	v_mfma_f32_16x16x32_bf16 v[36:39], v[146:149], v[214:217], v[36:39]
	v_mfma_f32_16x16x32_bf16 v[52:55], v[154:157], v[214:217], v[52:55]
	v_mfma_f32_16x16x32_bf16 v[32:35], v[146:149], v[222:225], v[32:35]
	v_mfma_f32_16x16x32_bf16 v[40:43], v[154:157], v[222:225], v[40:43]
	v_mfma_f32_16x16x32_bf16 v[56:59], v[150:153], v[202:205], v[56:59]
	v_mfma_f32_16x16x32_bf16 v[76:79], v[158:161], v[202:205], v[76:79]
	v_mfma_f32_16x16x32_bf16 v[44:47], v[150:153], v[210:213], v[44:47]
	v_mfma_f32_16x16x32_bf16 v[64:67], v[158:161], v[210:213], v[64:67]
	v_mfma_f32_16x16x32_bf16 v[36:39], v[150:153], v[218:221], v[36:39]
	v_mfma_f32_16x16x32_bf16 v[52:55], v[158:161], v[218:221], v[52:55]
	v_mfma_f32_16x16x32_bf16 v[32:35], v[150:153], v[226:229], v[32:35]
	v_mfma_f32_16x16x32_bf16 v[40:43], v[158:161], v[226:229], v[40:43]
	v_mfma_f32_16x16x32_bf16 v[112:115], v[162:165], v[198:201], v[112:115]
	v_mfma_f32_16x16x32_bf16 v[120:123], v[170:173], v[198:201], v[120:123]
	v_mfma_f32_16x16x32_bf16 v[104:107], v[162:165], v[206:209], v[104:107]
	v_mfma_f32_16x16x32_bf16 v[116:119], v[170:173], v[206:209], v[116:119]
	v_mfma_f32_16x16x32_bf16 v[100:103], v[162:165], v[214:217], v[100:103]
	v_mfma_f32_16x16x32_bf16 v[108:111], v[170:173], v[214:217], v[108:111]
	v_mfma_f32_16x16x32_bf16 v[96:99], v[162:165], v[222:225], v[96:99]
	v_mfma_f32_16x16x32_bf16 v[124:127], v[170:173], v[222:225], v[124:127]
	v_mfma_f32_16x16x32_bf16 v[112:115], v[166:169], v[202:205], v[112:115]
	v_mfma_f32_16x16x32_bf16 v[120:123], v[174:177], v[202:205], v[120:123]
	v_mfma_f32_16x16x32_bf16 v[104:107], v[166:169], v[210:213], v[104:107]
	v_mfma_f32_16x16x32_bf16 v[116:119], v[174:177], v[210:213], v[116:119]
	v_mfma_f32_16x16x32_bf16 v[100:103], v[166:169], v[218:221], v[100:103]
	v_mfma_f32_16x16x32_bf16 v[108:111], v[174:177], v[218:221], v[108:111]
	v_mfma_f32_16x16x32_bf16 v[96:99], v[166:169], v[226:229], v[96:99]
	v_mfma_f32_16x16x32_bf16 v[124:127], v[174:177], v[226:229], v[124:127]
	s_setprio 0
	s_barrier
	s_add_i32 s48, s48, 2
	s_add_u32 s46, s46, 0x100
	s_addc_u32 s47, s47, 0
	s_add_u32 s14, s14, 0x100
	s_addc_u32 s15, s15, 0
	s_cmp_gt_u32 s48, 13
	s_cbranch_scc0 .LBB0_395
	s_and_b64 vcc, exec, s[12:13]
	s_cbranch_vccz .LBB0_398
	s_barrier

.LBB0_451:
	s_add_i32 s60, s50, 2
	s_add_u32 s30, s8, 0x80
	s_addc_u32 s31, s9, 0
	s_add_i32 s61, 0, 0x10000
	s_cmp_eq_u32 s21, s50
	s_cselect_b32 s51, s47, s31
	s_cselect_b32 s50, s46, s30
	v_add_u32_e32 v128, s61, v173
	s_cselect_b32 s31, s49, vcc_lo
	s_cselect_b32 s30, s48, s45
	s_add_i32 vcc_hi, 0, 0x14000
	ds_read_b128 v[130:133], v128
	ds_read_b128 v[134:137], v128 offset:1024
	ds_read_b128 v[138:141], v128 offset:2048
	ds_read_b128 v[142:145], v128 offset:3072
	v_add_u32_e32 v128, vcc_hi, v173
	ds_read_b128 v[158:161], v128
	ds_read_b128 v[162:165], v128 offset:1024
	ds_read_b128 v[166:169], v128 offset:2048
	ds_read_b128 v[198:201], v128 offset:3072
	v_lshl_add_u64 v[170:171], s[8:9], 0, v[156:157]
	s_add_i32 m0, s85, 0xc000
	ds_read_b128 v[202:205], v190
	ds_read_b128 v[206:209], v190 offset:1024
	ds_read_b128 v[210:213], v190 offset:2048
	ds_read_b128 v[214:217], v190 offset:3072
	ds_read_b128 v[218:221], v190 offset:4096
	ds_read_b128 v[222:225], v190 offset:5120
	ds_read_b128 v[226:229], v190 offset:6144
	ds_read_b128 v[238:241], v190 offset:7168
	global_load_lds_dwordx4 v[170:171], off
	v_lshl_add_u64 v[170:171], s[8:9], 0, v[154:155]
	s_add_i32 m0, s85, 0xe000
	s_nop 0
	global_load_lds_dwordx4 v[170:171], off
	s_waitcnt vmcnt(8)
	s_waitcnt lgkmcnt(0)
	s_barrier
	s_setprio 1
	v_mfma_f32_16x16x32_bf16 v[124:127], v[130:133], v[202:205], v[124:127]
	v_mfma_f32_16x16x32_bf16 v[120:123], v[138:141], v[202:205], v[120:123]
	v_mfma_f32_16x16x32_bf16 v[108:111], v[130:133], v[210:213], v[108:111]
	v_mfma_f32_16x16x32_bf16 v[104:107], v[138:141], v[210:213], v[104:107]
	v_mfma_f32_16x16x32_bf16 v[92:95], v[130:133], v[218:221], v[92:95]
	v_mfma_f32_16x16x32_bf16 v[88:91], v[138:141], v[218:221], v[88:91]
	v_mfma_f32_16x16x32_bf16 v[76:79], v[130:133], v[226:229], v[76:79]
	v_mfma_f32_16x16x32_bf16 v[72:75], v[138:141], v[226:229], v[72:75]
	v_mfma_f32_16x16x32_bf16 v[124:127], v[134:137], v[206:209], v[124:127]
	v_mfma_f32_16x16x32_bf16 v[120:123], v[142:145], v[206:209], v[120:123]
	v_mfma_f32_16x16x32_bf16 v[108:111], v[134:137], v[214:217], v[108:111]
	v_mfma_f32_16x16x32_bf16 v[104:107], v[142:145], v[214:217], v[104:107]
	v_mfma_f32_16x16x32_bf16 v[92:95], v[134:137], v[222:225], v[92:95]
	v_mfma_f32_16x16x32_bf16 v[88:91], v[142:145], v[222:225], v[88:91]
	v_mfma_f32_16x16x32_bf16 v[76:79], v[134:137], v[238:241], v[76:79]
	v_mfma_f32_16x16x32_bf16 v[72:75], v[142:145], v[238:241], v[72:75]
	v_mfma_f32_16x16x32_bf16 v[116:119], v[158:161], v[202:205], v[116:119]
	v_mfma_f32_16x16x32_bf16 v[112:115], v[166:169], v[202:205], v[112:115]
	v_mfma_f32_16x16x32_bf16 v[100:103], v[158:161], v[210:213], v[100:103]
	v_mfma_f32_16x16x32_bf16 v[96:99], v[166:169], v[210:213], v[96:99]
	v_mfma_f32_16x16x32_bf16 v[84:87], v[158:161], v[218:221], v[84:87]
	v_mfma_f32_16x16x32_bf16 v[80:83], v[166:169], v[218:221], v[80:83]
	v_mfma_f32_16x16x32_bf16 v[68:71], v[158:161], v[226:229], v[68:71]
	v_mfma_f32_16x16x32_bf16 v[64:67], v[166:169], v[226:229], v[64:67]
	v_mfma_f32_16x16x32_bf16 v[116:119], v[162:165], v[206:209], v[116:119]
	v_mfma_f32_16x16x32_bf16 v[112:115], v[198:201], v[206:209], v[112:115]
	v_mfma_f32_16x16x32_bf16 v[100:103], v[162:165], v[214:217], v[100:103]
	v_mfma_f32_16x16x32_bf16 v[96:99], v[198:201], v[214:217], v[96:99]
	v_mfma_f32_16x16x32_bf16 v[84:87], v[162:165], v[222:225], v[84:87]
	v_mfma_f32_16x16x32_bf16 v[80:83], v[198:201], v[222:225], v[80:83]
	v_mfma_f32_16x16x32_bf16 v[68:71], v[162:165], v[238:241], v[68:71]
	v_mfma_f32_16x16x32_bf16 v[64:67], v[198:201], v[238:241], v[64:67]
	s_setprio 0
	s_barrier
	s_add_i32 s61, s61, s82
	v_lshl_add_u64 v[170:171], s[30:31], 0, v[148:149]
	s_mov_b32 m0, s61
	ds_read_b128 v[202:205], v190 offset:16384
	ds_read_b128 v[206:209], v190 offset:17408
	ds_read_b128 v[210:213], v190 offset:18432
	ds_read_b128 v[214:217], v190 offset:19456
	ds_read_b128 v[218:221], v190 offset:20480
	ds_read_b128 v[222:225], v190 offset:21504
	ds_read_b128 v[226:229], v190 offset:22528
	ds_read_b128 v[238:241], v190 offset:23552
	global_load_lds_dwordx4 v[170:171], off
	s_add_i32 m0, s61, 0x2000
	v_lshl_add_u64 v[242:243], s[30:31], 0, v[152:153]
	s_add_u32 s30, s30, s96
	s_addc_u32 s31, s31, 0
	s_add_i32 s61, vcc_hi, s82
	global_load_lds_dwordx4 v[242:243], off
	v_lshl_add_u64 v[244:245], s[30:31], 0, v[148:149]
	s_mov_b32 m0, s61
	v_lshl_add_u64 v[246:247], s[30:31], 0, v[152:153]
	global_load_lds_dwordx4 v[244:245], off
	s_add_i32 m0, s61, 0x2000
	v_lshl_add_u64 v[248:249], s[50:51], 0, v[146:147]
	global_load_lds_dwordx4 v[246:247], off
	s_mov_b32 m0, s85
	v_lshl_add_u64 v[250:251], s[50:51], 0, v[150:151]
	global_load_lds_dwordx4 v[248:249], off
	s_mov_b32 m0, s86
	s_nop 0
	global_load_lds_dwordx4 v[250:251], off
	s_waitcnt vmcnt(8)
	s_waitcnt lgkmcnt(0)
	s_barrier
	s_setprio 1
	v_mfma_f32_16x16x32_bf16 v[60:63], v[130:133], v[202:205], v[60:63]
	v_mfma_f32_16x16x32_bf16 v[56:59], v[138:141], v[202:205], v[56:59]
	v_mfma_f32_16x16x32_bf16 v[44:47], v[130:133], v[210:213], v[44:47]
	v_mfma_f32_16x16x32_bf16 v[40:43], v[138:141], v[210:213], v[40:43]
	v_mfma_f32_16x16x32_bf16 v[28:31], v[130:133], v[218:221], v[28:31]
	v_mfma_f32_16x16x32_bf16 v[24:27], v[138:141], v[218:221], v[24:27]
	v_mfma_f32_16x16x32_bf16 v[12:15], v[130:133], v[226:229], v[12:15]
	v_mfma_f32_16x16x32_bf16 v[8:11], v[138:141], v[226:229], v[8:11]
	v_mfma_f32_16x16x32_bf16 v[60:63], v[134:137], v[206:209], v[60:63]
	v_mfma_f32_16x16x32_bf16 v[56:59], v[142:145], v[206:209], v[56:59]
	v_mfma_f32_16x16x32_bf16 v[44:47], v[134:137], v[214:217], v[44:47]
	v_mfma_f32_16x16x32_bf16 v[40:43], v[142:145], v[214:217], v[40:43]
	v_mfma_f32_16x16x32_bf16 v[28:31], v[134:137], v[222:225], v[28:31]
	v_mfma_f32_16x16x32_bf16 v[24:27], v[142:145], v[222:225], v[24:27]
	v_mfma_f32_16x16x32_bf16 v[12:15], v[134:137], v[238:241], v[12:15]
	v_mfma_f32_16x16x32_bf16 v[8:11], v[142:145], v[238:241], v[8:11]
	v_mfma_f32_16x16x32_bf16 v[52:55], v[158:161], v[202:205], v[52:55]
	v_mfma_f32_16x16x32_bf16 v[48:51], v[166:169], v[202:205], v[48:51]
	v_mfma_f32_16x16x32_bf16 v[36:39], v[158:161], v[210:213], v[36:39]
	v_mfma_f32_16x16x32_bf16 v[32:35], v[166:169], v[210:213], v[32:35]
	v_mfma_f32_16x16x32_bf16 v[20:23], v[158:161], v[218:221], v[20:23]
	v_mfma_f32_16x16x32_bf16 v[16:19], v[166:169], v[218:221], v[16:19]
	v_mfma_f32_16x16x32_bf16 v[4:7], v[158:161], v[226:229], v[4:7]
	v_mfma_f32_16x16x32_bf16 v[0:3], v[166:169], v[226:229], v[0:3]
	v_mfma_f32_16x16x32_bf16 v[52:55], v[162:165], v[206:209], v[52:55]
	v_mfma_f32_16x16x32_bf16 v[48:51], v[198:201], v[206:209], v[48:51]
	v_mfma_f32_16x16x32_bf16 v[36:39], v[162:165], v[214:217], v[36:39]
	v_mfma_f32_16x16x32_bf16 v[32:35], v[198:201], v[214:217], v[32:35]
	v_mfma_f32_16x16x32_bf16 v[20:23], v[162:165], v[222:225], v[20:23]
	v_mfma_f32_16x16x32_bf16 v[16:19], v[198:201], v[222:225], v[16:19]
	v_mfma_f32_16x16x32_bf16 v[4:7], v[162:165], v[238:241], v[4:7]
	v_mfma_f32_16x16x32_bf16 v[0:3], v[198:201], v[238:241], v[0:3]
	s_setprio 0
	s_barrier
	s_add_i32 s61, 0, 0x18000
	v_add_u32_e32 v128, s61, v173
	s_add_i32 vcc_hi, 0, 0x1c000
	ds_read_b128 v[130:133], v128
	ds_read_b128 v[134:137], v128 offset:1024
	ds_read_b128 v[138:141], v128 offset:2048
	ds_read_b128 v[142:145], v128 offset:3072
	v_add_u32_e32 v128, vcc_hi, v173
	ds_read_b128 v[158:161], v128
	ds_read_b128 v[162:165], v128 offset:1024
	ds_read_b128 v[166:169], v128 offset:2048
	ds_read_b128 v[198:201], v128 offset:3072
	s_add_u32 s30, s50, s96
	s_addc_u32 s31, s51, 0
	s_mov_b32 m0, s87
	v_lshl_add_u64 v[252:253], s[30:31], 0, v[146:147]
	ds_read_b128 v[202:205], v190 offset:32768
	ds_read_b128 v[206:209], v190 offset:33792
	ds_read_b128 v[210:213], v190 offset:34816
	ds_read_b128 v[214:217], v190 offset:35840
	ds_read_b128 v[218:221], v190 offset:36864
	ds_read_b128 v[222:225], v190 offset:37888
	ds_read_b128 v[226:229], v190 offset:38912
	ds_read_b128 v[238:241], v190 offset:39936
	global_load_lds_dwordx4 v[252:253], off
	v_lshl_add_u64 v[252:253], s[30:31], 0, v[150:151]
	s_mov_b32 m0, s88
	s_nop 0
	global_load_lds_dwordx4 v[252:253], off
	s_waitcnt vmcnt(8)
	s_waitcnt lgkmcnt(0)
	s_barrier
	s_setprio 1
	v_mfma_f32_16x16x32_bf16 v[124:127], v[130:133], v[202:205], v[124:127]
	v_mfma_f32_16x16x32_bf16 v[120:123], v[138:141], v[202:205], v[120:123]
	v_mfma_f32_16x16x32_bf16 v[108:111], v[130:133], v[210:213], v[108:111]
	v_mfma_f32_16x16x32_bf16 v[104:107], v[138:141], v[210:213], v[104:107]
	v_mfma_f32_16x16x32_bf16 v[92:95], v[130:133], v[218:221], v[92:95]
	v_mfma_f32_16x16x32_bf16 v[88:91], v[138:141], v[218:221], v[88:91]
	v_mfma_f32_16x16x32_bf16 v[76:79], v[130:133], v[226:229], v[76:79]
	v_mfma_f32_16x16x32_bf16 v[72:75], v[138:141], v[226:229], v[72:75]
	v_mfma_f32_16x16x32_bf16 v[124:127], v[134:137], v[206:209], v[124:127]
	v_mfma_f32_16x16x32_bf16 v[120:123], v[142:145], v[206:209], v[120:123]
	v_mfma_f32_16x16x32_bf16 v[108:111], v[134:137], v[214:217], v[108:111]
	v_mfma_f32_16x16x32_bf16 v[104:107], v[142:145], v[214:217], v[104:107]
	v_mfma_f32_16x16x32_bf16 v[92:95], v[134:137], v[222:225], v[92:95]
	v_mfma_f32_16x16x32_bf16 v[88:91], v[142:145], v[222:225], v[88:91]
	v_mfma_f32_16x16x32_bf16 v[76:79], v[134:137], v[238:241], v[76:79]
	v_mfma_f32_16x16x32_bf16 v[72:75], v[142:145], v[238:241], v[72:75]
	v_mfma_f32_16x16x32_bf16 v[116:119], v[158:161], v[202:205], v[116:119]
	v_mfma_f32_16x16x32_bf16 v[112:115], v[166:169], v[202:205], v[112:115]
	v_mfma_f32_16x16x32_bf16 v[100:103], v[158:161], v[210:213], v[100:103]
	v_mfma_f32_16x16x32_bf16 v[96:99], v[166:169], v[210:213], v[96:99]
	v_mfma_f32_16x16x32_bf16 v[84:87], v[158:161], v[218:221], v[84:87]
	v_mfma_f32_16x16x32_bf16 v[80:83], v[166:169], v[218:221], v[80:83]
	v_mfma_f32_16x16x32_bf16 v[68:71], v[158:161], v[226:229], v[68:71]
	v_mfma_f32_16x16x32_bf16 v[64:67], v[166:169], v[226:229], v[64:67]
	v_mfma_f32_16x16x32_bf16 v[116:119], v[162:165], v[206:209], v[116:119]
	v_mfma_f32_16x16x32_bf16 v[112:115], v[198:201], v[206:209], v[112:115]
	v_mfma_f32_16x16x32_bf16 v[100:103], v[162:165], v[214:217], v[100:103]
	v_mfma_f32_16x16x32_bf16 v[96:99], v[198:201], v[214:217], v[96:99]
	v_mfma_f32_16x16x32_bf16 v[84:87], v[162:165], v[222:225], v[84:87]
	v_mfma_f32_16x16x32_bf16 v[80:83], v[198:201], v[222:225], v[80:83]
	v_mfma_f32_16x16x32_bf16 v[68:71], v[162:165], v[238:241], v[68:71]
	v_mfma_f32_16x16x32_bf16 v[64:67], v[198:201], v[238:241], v[64:67]
	s_setprio 0
	s_barrier
	s_add_i32 s30, s61, s82
	v_lshl_add_u64 v[170:171], v[170:171], 0, s[90:91]
	s_mov_b32 m0, s30
	ds_read_b128 v[202:205], v190 offset:49152
	ds_read_b128 v[206:209], v190 offset:50176
	ds_read_b128 v[210:213], v190 offset:51200
	ds_read_b128 v[214:217], v190 offset:52224
	ds_read_b128 v[218:221], v190 offset:53248
	ds_read_b128 v[222:225], v190 offset:54272
	ds_read_b128 v[226:229], v190 offset:55296
	ds_read_b128 v[238:241], v190 offset:56320
	global_load_lds_dwordx4 v[170:171], off
	v_lshl_add_u64 v[170:171], v[242:243], 0, s[90:91]
	s_add_i32 m0, s30, 0x2000
	s_add_i32 s30, vcc_hi, s82
	global_load_lds_dwordx4 v[170:171], off
	v_lshl_add_u64 v[170:171], v[244:245], 0, s[90:91]
	s_mov_b32 m0, s30
	s_nop 0
	global_load_lds_dwordx4 v[170:171], off
	v_lshl_add_u64 v[170:171], v[246:247], 0, s[90:91]
	s_add_i32 m0, s30, 0x2000
	s_nop 0
	global_load_lds_dwordx4 v[170:171], off
	v_lshl_add_u64 v[170:171], v[248:249], 0, s[90:91]
	s_mov_b32 m0, s53
	s_nop 0
	global_load_lds_dwordx4 v[170:171], off
	v_lshl_add_u64 v[170:171], v[250:251], 0, s[90:91]
	s_mov_b32 m0, s92
	s_nop 0
	global_load_lds_dwordx4 v[170:171], off
	s_waitcnt vmcnt(8)
	s_waitcnt lgkmcnt(0)
	s_barrier
	s_setprio 1
	v_mfma_f32_16x16x32_bf16 v[60:63], v[130:133], v[202:205], v[60:63]
	v_mfma_f32_16x16x32_bf16 v[56:59], v[138:141], v[202:205], v[56:59]
	v_mfma_f32_16x16x32_bf16 v[44:47], v[130:133], v[210:213], v[44:47]
	v_mfma_f32_16x16x32_bf16 v[40:43], v[138:141], v[210:213], v[40:43]
	v_mfma_f32_16x16x32_bf16 v[28:31], v[130:133], v[218:221], v[28:31]
	v_mfma_f32_16x16x32_bf16 v[24:27], v[138:141], v[218:221], v[24:27]
	v_mfma_f32_16x16x32_bf16 v[12:15], v[130:133], v[226:229], v[12:15]
	v_mfma_f32_16x16x32_bf16 v[8:11], v[138:141], v[226:229], v[8:11]
	v_mfma_f32_16x16x32_bf16 v[60:63], v[134:137], v[206:209], v[60:63]
	v_mfma_f32_16x16x32_bf16 v[56:59], v[142:145], v[206:209], v[56:59]
	v_mfma_f32_16x16x32_bf16 v[44:47], v[134:137], v[214:217], v[44:47]
	v_mfma_f32_16x16x32_bf16 v[40:43], v[142:145], v[214:217], v[40:43]
	v_mfma_f32_16x16x32_bf16 v[28:31], v[134:137], v[222:225], v[28:31]
	v_mfma_f32_16x16x32_bf16 v[24:27], v[142:145], v[222:225], v[24:27]
	v_mfma_f32_16x16x32_bf16 v[12:15], v[134:137], v[238:241], v[12:15]
	v_mfma_f32_16x16x32_bf16 v[8:11], v[142:145], v[238:241], v[8:11]
	v_mfma_f32_16x16x32_bf16 v[52:55], v[158:161], v[202:205], v[52:55]
	v_mfma_f32_16x16x32_bf16 v[48:51], v[166:169], v[202:205], v[48:51]
	v_mfma_f32_16x16x32_bf16 v[36:39], v[158:161], v[210:213], v[36:39]
	v_mfma_f32_16x16x32_bf16 v[32:35], v[166:169], v[210:213], v[32:35]
	v_mfma_f32_16x16x32_bf16 v[20:23], v[158:161], v[218:221], v[20:23]
	v_mfma_f32_16x16x32_bf16 v[16:19], v[166:169], v[218:221], v[16:19]
	v_mfma_f32_16x16x32_bf16 v[4:7], v[158:161], v[226:229], v[4:7]
	v_mfma_f32_16x16x32_bf16 v[0:3], v[166:169], v[226:229], v[0:3]
	v_mfma_f32_16x16x32_bf16 v[52:55], v[162:165], v[206:209], v[52:55]
	v_mfma_f32_16x16x32_bf16 v[48:51], v[198:201], v[206:209], v[48:51]
	v_mfma_f32_16x16x32_bf16 v[36:39], v[162:165], v[214:217], v[36:39]
	v_mfma_f32_16x16x32_bf16 v[32:35], v[198:201], v[214:217], v[32:35]
	v_mfma_f32_16x16x32_bf16 v[20:23], v[162:165], v[222:225], v[20:23]
	v_mfma_f32_16x16x32_bf16 v[16:19], v[198:201], v[222:225], v[16:19]
	v_mfma_f32_16x16x32_bf16 v[4:7], v[162:165], v[238:241], v[4:7]
	v_mfma_f32_16x16x32_bf16 v[0:3], v[198:201], v[238:241], v[0:3]
	s_setprio 0
	s_barrier
	s_add_u32 s45, s45, 0x100
	s_addc_u32 vcc_lo, vcc_lo, 0
	s_add_u32 s8, s8, 0x100
	s_addc_u32 s9, s9, 0
	s_cmp_ge_i32 s60, s5
	s_mov_b32 s50, s60
	s_cbranch_scc0 .LBB0_451

.LBB0_638:
	s_add_u32 s26, s24, 0xfffc0080
	s_addc_u32 s27, s25, -1
	s_add_i32 s30, 0, 0x10000
	s_cmp_eq_u32 s51, 12
	s_cselect_b32 s29, s15, s27
	s_cselect_b32 s28, s21, s26
	s_cselect_b32 s27, s13, s50
	s_cselect_b32 s26, s23, s49
	s_add_i32 s31, 0, 0x14000
	v_add_u32_e32 v156, s30, v145
	v_add_u32_e32 v172, s31, v145
	ds_read_b128 v[140:143], v156
	ds_read_b128 v[148:151], v156 offset:1024
	ds_read_b128 v[152:155], v156 offset:2048
	ds_read_b128 v[156:159], v156 offset:3072
	ds_read_b128 v[160:163], v172
	ds_read_b128 v[164:167], v172 offset:1024
	ds_read_b128 v[168:171], v172 offset:2048
	ds_read_b128 v[172:175], v172 offset:3072
	v_lshl_add_u64 v[176:177], s[24:25], 0, v[138:139]
	s_add_i32 m0, s1, 0xc000
	ds_read_b128 v[198:201], v147
	ds_read_b128 v[202:205], v147 offset:1024
	ds_read_b128 v[206:209], v147 offset:2048
	ds_read_b128 v[210:213], v147 offset:3072
	ds_read_b128 v[214:217], v147 offset:4096
	ds_read_b128 v[218:221], v147 offset:5120
	ds_read_b128 v[222:225], v147 offset:6144
	ds_read_b128 v[226:229], v147 offset:7168
	global_load_lds_dwordx4 v[176:177], off
	v_lshl_add_u64 v[176:177], s[24:25], 0, v[136:137]
	s_add_i32 m0, s1, 0xe000
	s_nop 0
	global_load_lds_dwordx4 v[176:177], off
	s_waitcnt vmcnt(8)
	s_waitcnt lgkmcnt(0)
	s_barrier
	s_setprio 1
	v_mfma_f32_16x16x32_bf16 v[120:123], v[140:143], v[198:201], v[120:123]
	v_mfma_f32_16x16x32_bf16 v[112:115], v[152:155], v[198:201], v[112:115]
	v_mfma_f32_16x16x32_bf16 v[104:107], v[140:143], v[206:209], v[104:107]
	v_mfma_f32_16x16x32_bf16 v[96:99], v[152:155], v[206:209], v[96:99]
	v_mfma_f32_16x16x32_bf16 v[88:91], v[140:143], v[214:217], v[88:91]
	v_mfma_f32_16x16x32_bf16 v[80:83], v[152:155], v[214:217], v[80:83]
	v_mfma_f32_16x16x32_bf16 v[72:75], v[140:143], v[222:225], v[72:75]
	v_mfma_f32_16x16x32_bf16 v[64:67], v[152:155], v[222:225], v[64:67]
	v_mfma_f32_16x16x32_bf16 v[120:123], v[148:151], v[202:205], v[120:123]
	v_mfma_f32_16x16x32_bf16 v[112:115], v[156:159], v[202:205], v[112:115]
	v_mfma_f32_16x16x32_bf16 v[104:107], v[148:151], v[210:213], v[104:107]
	v_mfma_f32_16x16x32_bf16 v[96:99], v[156:159], v[210:213], v[96:99]
	v_mfma_f32_16x16x32_bf16 v[88:91], v[148:151], v[218:221], v[88:91]
	v_mfma_f32_16x16x32_bf16 v[80:83], v[156:159], v[218:221], v[80:83]
	v_mfma_f32_16x16x32_bf16 v[72:75], v[148:151], v[226:229], v[72:75]
	v_mfma_f32_16x16x32_bf16 v[64:67], v[156:159], v[226:229], v[64:67]
	v_mfma_f32_16x16x32_bf16 v[124:127], v[160:163], v[198:201], v[124:127]
	v_mfma_f32_16x16x32_bf16 v[116:119], v[168:171], v[198:201], v[116:119]
	v_mfma_f32_16x16x32_bf16 v[108:111], v[160:163], v[206:209], v[108:111]
	v_mfma_f32_16x16x32_bf16 v[100:103], v[168:171], v[206:209], v[100:103]
	v_mfma_f32_16x16x32_bf16 v[92:95], v[160:163], v[214:217], v[92:95]
	v_mfma_f32_16x16x32_bf16 v[84:87], v[168:171], v[214:217], v[84:87]
	v_mfma_f32_16x16x32_bf16 v[76:79], v[160:163], v[222:225], v[76:79]
	v_mfma_f32_16x16x32_bf16 v[68:71], v[168:171], v[222:225], v[68:71]
	v_mfma_f32_16x16x32_bf16 v[124:127], v[164:167], v[202:205], v[124:127]
	v_mfma_f32_16x16x32_bf16 v[116:119], v[172:175], v[202:205], v[116:119]
	v_mfma_f32_16x16x32_bf16 v[108:111], v[164:167], v[210:213], v[108:111]
	v_mfma_f32_16x16x32_bf16 v[100:103], v[172:175], v[210:213], v[100:103]
	v_mfma_f32_16x16x32_bf16 v[92:95], v[164:167], v[218:221], v[92:95]
	v_mfma_f32_16x16x32_bf16 v[84:87], v[172:175], v[218:221], v[84:87]
	v_mfma_f32_16x16x32_bf16 v[76:79], v[164:167], v[226:229], v[76:79]
	v_mfma_f32_16x16x32_bf16 v[68:71], v[172:175], v[226:229], v[68:71]
	s_setprio 0
	s_barrier
	s_add_i32 s30, s30, s45
	v_lshl_add_u64 v[176:177], s[26:27], 0, v[128:129]
	s_mov_b32 m0, s30
	ds_read_b128 v[198:201], v147 offset:16384
	ds_read_b128 v[202:205], v147 offset:17408
	ds_read_b128 v[206:209], v147 offset:18432
	ds_read_b128 v[210:213], v147 offset:19456
	ds_read_b128 v[214:217], v147 offset:20480
	ds_read_b128 v[218:221], v147 offset:21504
	ds_read_b128 v[222:225], v147 offset:22528
	ds_read_b128 v[226:229], v147 offset:23552
	global_load_lds_dwordx4 v[176:177], off
	s_add_i32 m0, s30, 0x2000
	s_add_u32 s52, s26, 0x40000
	v_lshl_add_u64 v[238:239], s[26:27], 0, v[130:131]
	s_addc_u32 s53, s27, 0
	s_add_i32 s30, s31, s45
	global_load_lds_dwordx4 v[238:239], off
	v_lshl_add_u64 v[240:241], s[52:53], 0, v[128:129]
	s_mov_b32 m0, s30
	v_lshl_add_u64 v[242:243], s[28:29], 0, v[132:133]
	global_load_lds_dwordx4 v[240:241], off
	v_lshl_add_u64 v[240:241], s[52:53], 0, v[130:131]
	s_add_i32 m0, s30, 0x2000
	s_nop 0
	global_load_lds_dwordx4 v[240:241], off
	v_lshl_add_u64 v[240:241], s[28:29], 0, v[134:135]
	s_mov_b32 m0, s1
	s_nop 0
	global_load_lds_dwordx4 v[240:241], off
	s_mov_b32 m0, s43
	s_nop 0
	global_load_lds_dwordx4 v[242:243], off
	s_waitcnt vmcnt(8)
	s_waitcnt lgkmcnt(0)
	s_barrier
	s_setprio 1
	v_mfma_f32_16x16x32_bf16 v[56:59], v[140:143], v[198:201], v[56:59]
	v_mfma_f32_16x16x32_bf16 v[48:51], v[152:155], v[198:201], v[48:51]
	v_mfma_f32_16x16x32_bf16 v[40:43], v[140:143], v[206:209], v[40:43]
	v_mfma_f32_16x16x32_bf16 v[32:35], v[152:155], v[206:209], v[32:35]
	v_mfma_f32_16x16x32_bf16 v[24:27], v[140:143], v[214:217], v[24:27]
	v_mfma_f32_16x16x32_bf16 v[16:19], v[152:155], v[214:217], v[16:19]
	v_mfma_f32_16x16x32_bf16 v[8:11], v[140:143], v[222:225], v[8:11]
	v_mfma_f32_16x16x32_bf16 v[0:3], v[152:155], v[222:225], v[0:3]
	v_mfma_f32_16x16x32_bf16 v[56:59], v[148:151], v[202:205], v[56:59]
	v_mfma_f32_16x16x32_bf16 v[48:51], v[156:159], v[202:205], v[48:51]
	v_mfma_f32_16x16x32_bf16 v[40:43], v[148:151], v[210:213], v[40:43]
	v_mfma_f32_16x16x32_bf16 v[32:35], v[156:159], v[210:213], v[32:35]
	v_mfma_f32_16x16x32_bf16 v[24:27], v[148:151], v[218:221], v[24:27]
	v_mfma_f32_16x16x32_bf16 v[16:19], v[156:159], v[218:221], v[16:19]
	v_mfma_f32_16x16x32_bf16 v[8:11], v[148:151], v[226:229], v[8:11]
	v_mfma_f32_16x16x32_bf16 v[0:3], v[156:159], v[226:229], v[0:3]
	v_mfma_f32_16x16x32_bf16 v[60:63], v[160:163], v[198:201], v[60:63]
	v_mfma_f32_16x16x32_bf16 v[52:55], v[168:171], v[198:201], v[52:55]
	v_mfma_f32_16x16x32_bf16 v[44:47], v[160:163], v[206:209], v[44:47]
	v_mfma_f32_16x16x32_bf16 v[36:39], v[168:171], v[206:209], v[36:39]
	v_mfma_f32_16x16x32_bf16 v[28:31], v[160:163], v[214:217], v[28:31]
	v_mfma_f32_16x16x32_bf16 v[20:23], v[168:171], v[214:217], v[20:23]
	v_mfma_f32_16x16x32_bf16 v[12:15], v[160:163], v[222:225], v[12:15]
	v_mfma_f32_16x16x32_bf16 v[4:7], v[168:171], v[222:225], v[4:7]
	v_mfma_f32_16x16x32_bf16 v[60:63], v[164:167], v[202:205], v[60:63]
	v_mfma_f32_16x16x32_bf16 v[52:55], v[172:175], v[202:205], v[52:55]
	v_mfma_f32_16x16x32_bf16 v[44:47], v[164:167], v[210:213], v[44:47]
	v_mfma_f32_16x16x32_bf16 v[36:39], v[172:175], v[210:213], v[36:39]
	v_mfma_f32_16x16x32_bf16 v[28:31], v[164:167], v[218:221], v[28:31]
	v_mfma_f32_16x16x32_bf16 v[20:23], v[172:175], v[218:221], v[20:23]
	v_mfma_f32_16x16x32_bf16 v[12:15], v[164:167], v[226:229], v[12:15]
	v_mfma_f32_16x16x32_bf16 v[4:7], v[172:175], v[226:229], v[4:7]
	s_setprio 0
	s_barrier
	s_add_i32 s30, 0, 0x18000
	s_add_i32 s31, 0, 0x1c000
	v_add_u32_e32 v156, s30, v145
	v_add_u32_e32 v172, s31, v145
	ds_read_b128 v[140:143], v156
	ds_read_b128 v[148:151], v156 offset:1024
	ds_read_b128 v[152:155], v156 offset:2048
	ds_read_b128 v[156:159], v156 offset:3072
	ds_read_b128 v[160:163], v172
	ds_read_b128 v[164:167], v172 offset:1024
	ds_read_b128 v[168:171], v172 offset:2048
	ds_read_b128 v[172:175], v172 offset:3072
	s_add_u32 s28, s28, 0x40000
	s_addc_u32 s29, s29, 0
	s_mov_b32 m0, s46
	v_lshl_add_u64 v[244:245], s[28:29], 0, v[134:135]
	ds_read_b128 v[198:201], v147 offset:32768
	ds_read_b128 v[202:205], v147 offset:33792
	ds_read_b128 v[206:209], v147 offset:34816
	ds_read_b128 v[210:213], v147 offset:35840
	ds_read_b128 v[214:217], v147 offset:36864
	ds_read_b128 v[218:221], v147 offset:37888
	ds_read_b128 v[222:225], v147 offset:38912
	ds_read_b128 v[226:229], v147 offset:39936
	global_load_lds_dwordx4 v[244:245], off
	v_lshl_add_u64 v[244:245], s[28:29], 0, v[132:133]
	s_mov_b32 m0, s47
	s_nop 0
	global_load_lds_dwordx4 v[244:245], off
	s_waitcnt vmcnt(8)
	s_waitcnt lgkmcnt(0)
	s_barrier
	s_setprio 1
	v_mfma_f32_16x16x32_bf16 v[120:123], v[140:143], v[198:201], v[120:123]
	v_mfma_f32_16x16x32_bf16 v[112:115], v[152:155], v[198:201], v[112:115]
	v_mfma_f32_16x16x32_bf16 v[104:107], v[140:143], v[206:209], v[104:107]
	v_mfma_f32_16x16x32_bf16 v[96:99], v[152:155], v[206:209], v[96:99]
	v_mfma_f32_16x16x32_bf16 v[88:91], v[140:143], v[214:217], v[88:91]
	v_mfma_f32_16x16x32_bf16 v[80:83], v[152:155], v[214:217], v[80:83]
	v_mfma_f32_16x16x32_bf16 v[72:75], v[140:143], v[222:225], v[72:75]
	v_mfma_f32_16x16x32_bf16 v[64:67], v[152:155], v[222:225], v[64:67]
	v_mfma_f32_16x16x32_bf16 v[120:123], v[148:151], v[202:205], v[120:123]
	v_mfma_f32_16x16x32_bf16 v[112:115], v[156:159], v[202:205], v[112:115]
	v_mfma_f32_16x16x32_bf16 v[104:107], v[148:151], v[210:213], v[104:107]
	v_mfma_f32_16x16x32_bf16 v[96:99], v[156:159], v[210:213], v[96:99]
	v_mfma_f32_16x16x32_bf16 v[88:91], v[148:151], v[218:221], v[88:91]
	v_mfma_f32_16x16x32_bf16 v[80:83], v[156:159], v[218:221], v[80:83]
	v_mfma_f32_16x16x32_bf16 v[72:75], v[148:151], v[226:229], v[72:75]
	v_mfma_f32_16x16x32_bf16 v[64:67], v[156:159], v[226:229], v[64:67]
	v_mfma_f32_16x16x32_bf16 v[124:127], v[160:163], v[198:201], v[124:127]
	v_mfma_f32_16x16x32_bf16 v[116:119], v[168:171], v[198:201], v[116:119]
	v_mfma_f32_16x16x32_bf16 v[108:111], v[160:163], v[206:209], v[108:111]
	v_mfma_f32_16x16x32_bf16 v[100:103], v[168:171], v[206:209], v[100:103]
	v_mfma_f32_16x16x32_bf16 v[92:95], v[160:163], v[214:217], v[92:95]
	v_mfma_f32_16x16x32_bf16 v[84:87], v[168:171], v[214:217], v[84:87]
	v_mfma_f32_16x16x32_bf16 v[76:79], v[160:163], v[222:225], v[76:79]
	v_mfma_f32_16x16x32_bf16 v[68:71], v[168:171], v[222:225], v[68:71]
	v_mfma_f32_16x16x32_bf16 v[124:127], v[164:167], v[202:205], v[124:127]
	v_mfma_f32_16x16x32_bf16 v[116:119], v[172:175], v[202:205], v[116:119]
	v_mfma_f32_16x16x32_bf16 v[108:111], v[164:167], v[210:213], v[108:111]
	v_mfma_f32_16x16x32_bf16 v[100:103], v[172:175], v[210:213], v[100:103]
	v_mfma_f32_16x16x32_bf16 v[92:95], v[164:167], v[218:221], v[92:95]
	v_mfma_f32_16x16x32_bf16 v[84:87], v[172:175], v[218:221], v[84:87]
	v_mfma_f32_16x16x32_bf16 v[76:79], v[164:167], v[226:229], v[76:79]
	v_mfma_f32_16x16x32_bf16 v[68:71], v[172:175], v[226:229], v[68:71]
	s_setprio 0
	s_barrier
	s_add_i32 s28, s30, s45
	v_lshl_add_u64 v[176:177], v[176:177], 0, s[90:91]
	s_mov_b32 m0, s28
	ds_read_b128 v[198:201], v147 offset:49152
	ds_read_b128 v[202:205], v147 offset:50176
	ds_read_b128 v[206:209], v147 offset:51200
	ds_read_b128 v[210:213], v147 offset:52224
	ds_read_b128 v[214:217], v147 offset:53248
	ds_read_b128 v[218:221], v147 offset:54272
	ds_read_b128 v[222:225], v147 offset:55296
	ds_read_b128 v[226:229], v147 offset:56320
	global_load_lds_dwordx4 v[176:177], off
	s_add_i32 m0, s28, 0x2000
	s_add_u32 s26, s26, 0x40080
	v_lshl_add_u64 v[176:177], v[238:239], 0, s[90:91]
	s_addc_u32 s27, s27, 0
	s_add_i32 s28, s31, s45
	global_load_lds_dwordx4 v[176:177], off
	v_lshl_add_u64 v[176:177], s[26:27], 0, v[128:129]
	s_mov_b32 m0, s28
	s_nop 0
	global_load_lds_dwordx4 v[176:177], off
	v_lshl_add_u64 v[176:177], s[26:27], 0, v[130:131]
	s_add_i32 m0, s28, 0x2000
	s_nop 0
	global_load_lds_dwordx4 v[176:177], off
	v_lshl_add_u64 v[176:177], v[240:241], 0, s[90:91]
	s_mov_b32 m0, s0
	s_nop 0
	global_load_lds_dwordx4 v[176:177], off
	v_lshl_add_u64 v[176:177], v[242:243], 0, s[90:91]
	s_mov_b32 m0, s4
	s_nop 0
	global_load_lds_dwordx4 v[176:177], off
	s_waitcnt vmcnt(8)
	s_waitcnt lgkmcnt(0)
	s_barrier
	s_setprio 1
	v_mfma_f32_16x16x32_bf16 v[56:59], v[140:143], v[198:201], v[56:59]
	v_mfma_f32_16x16x32_bf16 v[48:51], v[152:155], v[198:201], v[48:51]
	v_mfma_f32_16x16x32_bf16 v[40:43], v[140:143], v[206:209], v[40:43]
	v_mfma_f32_16x16x32_bf16 v[32:35], v[152:155], v[206:209], v[32:35]
	v_mfma_f32_16x16x32_bf16 v[24:27], v[140:143], v[214:217], v[24:27]
	v_mfma_f32_16x16x32_bf16 v[16:19], v[152:155], v[214:217], v[16:19]
	v_mfma_f32_16x16x32_bf16 v[8:11], v[140:143], v[222:225], v[8:11]
	v_mfma_f32_16x16x32_bf16 v[0:3], v[152:155], v[222:225], v[0:3]
	v_mfma_f32_16x16x32_bf16 v[56:59], v[148:151], v[202:205], v[56:59]
	v_mfma_f32_16x16x32_bf16 v[48:51], v[156:159], v[202:205], v[48:51]
	v_mfma_f32_16x16x32_bf16 v[40:43], v[148:151], v[210:213], v[40:43]
	v_mfma_f32_16x16x32_bf16 v[32:35], v[156:159], v[210:213], v[32:35]
	v_mfma_f32_16x16x32_bf16 v[24:27], v[148:151], v[218:221], v[24:27]
	v_mfma_f32_16x16x32_bf16 v[16:19], v[156:159], v[218:221], v[16:19]
	v_mfma_f32_16x16x32_bf16 v[8:11], v[148:151], v[226:229], v[8:11]
	v_mfma_f32_16x16x32_bf16 v[0:3], v[156:159], v[226:229], v[0:3]
	v_mfma_f32_16x16x32_bf16 v[60:63], v[160:163], v[198:201], v[60:63]
	v_mfma_f32_16x16x32_bf16 v[52:55], v[168:171], v[198:201], v[52:55]
	v_mfma_f32_16x16x32_bf16 v[44:47], v[160:163], v[206:209], v[44:47]
	v_mfma_f32_16x16x32_bf16 v[36:39], v[168:171], v[206:209], v[36:39]
	v_mfma_f32_16x16x32_bf16 v[28:31], v[160:163], v[214:217], v[28:31]
	v_mfma_f32_16x16x32_bf16 v[20:23], v[168:171], v[214:217], v[20:23]
	v_mfma_f32_16x16x32_bf16 v[12:15], v[160:163], v[222:225], v[12:15]
	v_mfma_f32_16x16x32_bf16 v[4:7], v[168:171], v[222:225], v[4:7]
	v_mfma_f32_16x16x32_bf16 v[60:63], v[164:167], v[202:205], v[60:63]
	v_mfma_f32_16x16x32_bf16 v[52:55], v[172:175], v[202:205], v[52:55]
	v_mfma_f32_16x16x32_bf16 v[44:47], v[164:167], v[210:213], v[44:47]
	v_mfma_f32_16x16x32_bf16 v[36:39], v[172:175], v[210:213], v[36:39]
	v_mfma_f32_16x16x32_bf16 v[28:31], v[164:167], v[218:221], v[28:31]
	v_mfma_f32_16x16x32_bf16 v[20:23], v[172:175], v[218:221], v[20:23]
	v_mfma_f32_16x16x32_bf16 v[12:15], v[164:167], v[226:229], v[12:15]
	v_mfma_f32_16x16x32_bf16 v[4:7], v[172:175], v[226:229], v[4:7]
	s_setprio 0
	s_barrier
	s_add_i32 s51, s51, 2
	s_add_u32 s49, s49, 0x100
	s_addc_u32 s50, s50, 0
	s_add_u32 s24, s24, 0x100
	s_addc_u32 s25, s25, 0
	s_cmp_gt_u32 s51, 13
	s_cbranch_scc0 .LBB0_638
	s_and_b64 vcc, exec, s[10:11]
	s_cbranch_vccz .LBB0_641
	s_barrier
